# GEMM phases: per-cluster s_setprio toggles removed; one static s_setprio 1 for waves 4-7 per GEMM phase (set at the phase-loop head)
# baseline (speedup 1.0000x reference)
.LBB0_24:
	s_mov_b32 s72, s34
	v_readlane_b32 s20, v254, 0
	s_cmp_lg_u32 s70, 0
	s_mov_b64 s[2:3], -1
	s_cbranch_scc0 .LBB0_477
	s_add_i32 s2, s70, -1
	s_mul_hi_i32 s3, s2, 0x92492493
	s_add_i32 s3, s3, s2
	s_lshr_b32 s4, s3, 31
	s_ashr_i32 s3, s3, 2
	s_add_i32 s24, s3, s4
	s_mul_i32 s3, s24, 7
	s_sub_i32 s11, s2, s3
	s_setprio 0
	s_cmp_eq_u32 s11, 0
	s_cbranch_scc1 .Lsp_gemm
	s_cmp_lt_u32 s11, 4
	s_cbranch_scc1 .Lsp_done
.Lsp_gemm:
	v_readfirstlane_b32 s100, v206
	s_nop 3
	s_cmp_lt_u32 s100, 0x100
	s_cbranch_scc1 .Lsp_done
	s_setprio 1
.Lsp_done:
	s_mov_b64 s[2:3], -1
	s_mov_b64 s[82:83], 0
	s_cmp_lt_i32 s11, 3
	s_mov_b64 s[28:29], 0
	s_cbranch_scc1 .LBB0_175
	s_cmp_gt_i32 s11, 3
	s_cbranch_scc0 .LBB0_165
	s_cmp_gt_i32 s11, 4
	s_cbranch_scc0 .LBB0_147
	s_cmp_eq_u32 s11, 5
	s_mov_b64 s[28:29], -1
	s_cbranch_scc0 .LBB0_146
	v_readlane_b32 s5, v254, 0
	s_cmpk_lt_i32 s5, 0x100
	s_cselect_b64 s[2:3], -1, 0
	s_cmpk_gt_i32 s5, 0xff
	s_cbranch_scc1 .LBB0_35
	s_ashr_i32 s4, s5, 31
	s_lshr_b32 s4, s4, 29
	s_add_i32 s6, s5, s4
	s_and_b32 s4, s6, -8
	s_sub_i32 s7, s5, s4
	s_cmp_gt_i32 s7, -1
	s_mov_b64 s[4:5], -1
	s_cbranch_scc0 .LBB0_32
	s_lshl_b32 s8, s7, 5
	s_mov_b64 s[4:5], 0

.LBB0_42:
	s_add_u32 s8, s4, s2
	s_addc_u32 s9, s5, 0
	s_add_u32 s3, s8, 0x100
	s_addc_u32 s10, s9, 0
	s_and_b64 s[6:7], s[84:85], exec
	s_cselect_b32 s7, s87, s10
	s_cselect_b32 s6, s86, s3
	s_add_u32 s2, s36, s2
	s_addc_u32 s3, s37, 0
	s_add_u32 s10, s2, 0x100
	ds_read_b128 v[128:131], v221
	ds_read_b128 v[132:135], v222
	ds_read_b128 v[136:139], v223
	ds_read_b128 v[140:143], v224
	ds_read_b128 v[144:147], v225
	ds_read_b128 v[148:151], v226
	ds_read_b128 v[152:155], v227
	ds_read_b128 v[156:159], v228
	s_addc_u32 s11, s3, 0
	s_and_b64 s[2:3], s[84:85], exec
	s_cselect_b32 vcc_hi, s89, s11
	s_cselect_b32 vcc_lo, s88, s10
	s_add_u32 s10, s8, 0x30080
	s_addc_u32 s11, s9, 0
	s_add_u32 s8, vcc_lo, 0x10000
	s_addc_u32 s9, vcc_hi, 0
	s_add_u32 s2, s6, 0x30000
	s_addc_u32 s3, s7, 0
	s_add_u32 s84, vcc_lo, 0x10080
	s_addc_u32 s85, vcc_hi, 0
	s_mov_b32 m0, s19
	ds_read_b128 v[160:163], v219
	ds_read_b128 v[164:167], v219 offset:1024
	ds_read_b128 v[168:171], v219 offset:2048
	ds_read_b128 v[172:175], v219 offset:3072
	ds_read_b128 v[198:201], v219 offset:4096
	ds_read_b128 v[202:205], v219 offset:5120
	ds_read_b128 v[238:241], v219 offset:6144
	ds_read_b128 v[242:245], v219 offset:7168
	global_load_lds_dwordx4 v192, s[10:11]
	s_mov_b32 m0, s74
	s_nop 0
	global_load_lds_dwordx4 v188, s[10:11]
	s_waitcnt vmcnt(8)
	s_waitcnt lgkmcnt(0)
	s_barrier
	s_waitcnt lgkmcnt(0)
	v_mfma_f32_16x16x32_bf16 v[104:107], v[128:131], v[160:163], v[104:107]
	v_mfma_f32_16x16x32_bf16 v[124:127], v[136:139], v[160:163], v[124:127]
	v_mfma_f32_16x16x32_bf16 v[96:99], v[128:131], v[168:171], v[96:99]
	v_mfma_f32_16x16x32_bf16 v[120:123], v[136:139], v[168:171], v[120:123]
	v_mfma_f32_16x16x32_bf16 v[88:91], v[128:131], v[198:201], v[88:91]
	v_mfma_f32_16x16x32_bf16 v[116:119], v[136:139], v[198:201], v[116:119]
	v_mfma_f32_16x16x32_bf16 v[80:83], v[128:131], v[238:241], v[80:83]
	v_mfma_f32_16x16x32_bf16 v[112:115], v[136:139], v[238:241], v[112:115]
	v_mfma_f32_16x16x32_bf16 v[104:107], v[132:135], v[164:167], v[104:107]
	v_mfma_f32_16x16x32_bf16 v[124:127], v[140:143], v[164:167], v[124:127]
	v_mfma_f32_16x16x32_bf16 v[96:99], v[132:135], v[172:175], v[96:99]
	v_mfma_f32_16x16x32_bf16 v[120:123], v[140:143], v[172:175], v[120:123]
	v_mfma_f32_16x16x32_bf16 v[88:91], v[132:135], v[202:205], v[88:91]
	v_mfma_f32_16x16x32_bf16 v[116:119], v[140:143], v[202:205], v[116:119]
	v_mfma_f32_16x16x32_bf16 v[80:83], v[132:135], v[242:245], v[80:83]
	v_mfma_f32_16x16x32_bf16 v[112:115], v[140:143], v[242:245], v[112:115]
	v_mfma_f32_16x16x32_bf16 v[72:75], v[144:147], v[160:163], v[72:75]
	v_mfma_f32_16x16x32_bf16 v[108:111], v[152:155], v[160:163], v[108:111]
	v_mfma_f32_16x16x32_bf16 v[64:67], v[144:147], v[168:171], v[64:67]
	v_mfma_f32_16x16x32_bf16 v[100:103], v[152:155], v[168:171], v[100:103]
	v_mfma_f32_16x16x32_bf16 v[56:59], v[144:147], v[198:201], v[56:59]
	v_mfma_f32_16x16x32_bf16 v[92:95], v[152:155], v[198:201], v[92:95]
	v_mfma_f32_16x16x32_bf16 v[48:51], v[144:147], v[238:241], v[48:51]
	v_mfma_f32_16x16x32_bf16 v[84:87], v[152:155], v[238:241], v[84:87]
	v_mfma_f32_16x16x32_bf16 v[72:75], v[148:151], v[164:167], v[72:75]
	v_mfma_f32_16x16x32_bf16 v[108:111], v[156:159], v[164:167], v[108:111]
	v_mfma_f32_16x16x32_bf16 v[64:67], v[148:151], v[172:175], v[64:67]
	v_mfma_f32_16x16x32_bf16 v[100:103], v[156:159], v[172:175], v[100:103]
	v_mfma_f32_16x16x32_bf16 v[56:59], v[148:151], v[202:205], v[56:59]
	v_mfma_f32_16x16x32_bf16 v[92:95], v[156:159], v[202:205], v[92:95]
	v_mfma_f32_16x16x32_bf16 v[48:51], v[148:151], v[242:245], v[48:51]
	v_mfma_f32_16x16x32_bf16 v[84:87], v[156:159], v[242:245], v[84:87]
	s_barrier
	s_mov_b32 m0, s23
	v_lshl_add_u64 v[246:247], vcc, 0, v[190:191]
	ds_read_b128 v[160:163], v219 offset:16384
	ds_read_b128 v[164:167], v219 offset:17408
	ds_read_b128 v[168:171], v219 offset:18432
	ds_read_b128 v[172:175], v219 offset:19456
	ds_read_b128 v[198:201], v219 offset:20480
	ds_read_b128 v[202:205], v219 offset:21504
	ds_read_b128 v[238:241], v219 offset:22528
	ds_read_b128 v[242:245], v219 offset:23552
	global_load_lds_dwordx4 v[246:247], off
	v_lshl_add_u64 v[248:249], vcc, 0, v[186:187]
	s_mov_b32 m0, s91
	s_nop 0
	global_load_lds_dwordx4 v[248:249], off
	s_mov_b32 m0, s21
	v_lshl_add_u64 v[252:253], s[6:7], 0, v[188:189]
	global_load_lds_dwordx4 v190, s[8:9]
	s_mov_b32 m0, s27
	s_nop 0
	global_load_lds_dwordx4 v186, s[8:9]
	v_lshl_add_u64 v[250:251], s[6:7], 0, v[192:193]
	s_mov_b32 m0, s43
	s_nop 0
	global_load_lds_dwordx4 v[250:251], off
	s_mov_b32 m0, s26
	s_nop 0
	global_load_lds_dwordx4 v[252:253], off
	s_waitcnt vmcnt(8)
	s_waitcnt lgkmcnt(0)
	s_barrier
	s_waitcnt lgkmcnt(0)
	v_mfma_f32_16x16x32_bf16 v[40:43], v[128:131], v[160:163], v[40:43]
	v_mfma_f32_16x16x32_bf16 v[76:79], v[136:139], v[160:163], v[76:79]
	v_mfma_f32_16x16x32_bf16 v[32:35], v[128:131], v[168:171], v[32:35]
	v_mfma_f32_16x16x32_bf16 v[68:71], v[136:139], v[168:171], v[68:71]
	v_mfma_f32_16x16x32_bf16 v[24:27], v[128:131], v[198:201], v[24:27]
	v_mfma_f32_16x16x32_bf16 v[60:63], v[136:139], v[198:201], v[60:63]
	v_mfma_f32_16x16x32_bf16 v[20:23], v[128:131], v[238:241], v[20:23]
	v_mfma_f32_16x16x32_bf16 v[52:55], v[136:139], v[238:241], v[52:55]
	v_mfma_f32_16x16x32_bf16 v[40:43], v[132:135], v[164:167], v[40:43]
	v_mfma_f32_16x16x32_bf16 v[76:79], v[140:143], v[164:167], v[76:79]
	v_mfma_f32_16x16x32_bf16 v[32:35], v[132:135], v[172:175], v[32:35]
	v_mfma_f32_16x16x32_bf16 v[68:71], v[140:143], v[172:175], v[68:71]
	v_mfma_f32_16x16x32_bf16 v[24:27], v[132:135], v[202:205], v[24:27]
	v_mfma_f32_16x16x32_bf16 v[60:63], v[140:143], v[202:205], v[60:63]
	v_mfma_f32_16x16x32_bf16 v[20:23], v[132:135], v[242:245], v[20:23]
	v_mfma_f32_16x16x32_bf16 v[52:55], v[140:143], v[242:245], v[52:55]
	v_mfma_f32_16x16x32_bf16 v[16:19], v[144:147], v[160:163], v[16:19]
	v_mfma_f32_16x16x32_bf16 v[44:47], v[152:155], v[160:163], v[44:47]
	v_mfma_f32_16x16x32_bf16 v[12:15], v[144:147], v[168:171], v[12:15]
	v_mfma_f32_16x16x32_bf16 v[36:39], v[152:155], v[168:171], v[36:39]
	v_mfma_f32_16x16x32_bf16 v[4:7], v[144:147], v[198:201], v[4:7]
	v_mfma_f32_16x16x32_bf16 v[28:31], v[152:155], v[198:201], v[28:31]
	v_mfma_f32_16x16x32_bf16 v[0:3], v[144:147], v[238:241], v[0:3]
	v_mfma_f32_16x16x32_bf16 v[8:11], v[152:155], v[238:241], v[8:11]
	v_mfma_f32_16x16x32_bf16 v[16:19], v[148:151], v[164:167], v[16:19]
	v_mfma_f32_16x16x32_bf16 v[44:47], v[156:159], v[164:167], v[44:47]
	v_mfma_f32_16x16x32_bf16 v[12:15], v[148:151], v[172:175], v[12:15]
	v_mfma_f32_16x16x32_bf16 v[36:39], v[156:159], v[172:175], v[36:39]
	v_mfma_f32_16x16x32_bf16 v[4:7], v[148:151], v[202:205], v[4:7]
	v_mfma_f32_16x16x32_bf16 v[28:31], v[156:159], v[202:205], v[28:31]
	v_mfma_f32_16x16x32_bf16 v[0:3], v[148:151], v[242:245], v[0:3]
	v_mfma_f32_16x16x32_bf16 v[8:11], v[156:159], v[242:245], v[8:11]
	s_barrier
	ds_read_b128 v[128:131], v229
	ds_read_b128 v[132:135], v230
	ds_read_b128 v[136:139], v231
	ds_read_b128 v[140:143], v232
	ds_read_b128 v[144:147], v233
	ds_read_b128 v[148:151], v234
	ds_read_b128 v[152:155], v235
	ds_read_b128 v[156:159], v236
	s_mov_b32 m0, s29
	ds_read_b128 v[160:163], v219 offset:32768
	ds_read_b128 v[164:167], v219 offset:33792
	ds_read_b128 v[168:171], v219 offset:34816
	ds_read_b128 v[172:175], v219 offset:35840
	ds_read_b128 v[198:201], v219 offset:36864
	ds_read_b128 v[202:205], v219 offset:37888
	ds_read_b128 v[238:241], v219 offset:38912
	ds_read_b128 v[242:245], v219 offset:39936
	global_load_lds_dwordx4 v192, s[2:3]
	s_mov_b32 m0, s28
	s_nop 0
	global_load_lds_dwordx4 v188, s[2:3]
	s_waitcnt vmcnt(8)
	s_waitcnt lgkmcnt(0)
	s_barrier
	s_waitcnt lgkmcnt(0)
	v_mfma_f32_16x16x32_bf16 v[104:107], v[128:131], v[160:163], v[104:107]
	v_mfma_f32_16x16x32_bf16 v[124:127], v[136:139], v[160:163], v[124:127]
	v_mfma_f32_16x16x32_bf16 v[96:99], v[128:131], v[168:171], v[96:99]
	v_mfma_f32_16x16x32_bf16 v[120:123], v[136:139], v[168:171], v[120:123]
	v_mfma_f32_16x16x32_bf16 v[88:91], v[128:131], v[198:201], v[88:91]
	v_mfma_f32_16x16x32_bf16 v[116:119], v[136:139], v[198:201], v[116:119]
	v_mfma_f32_16x16x32_bf16 v[80:83], v[128:131], v[238:241], v[80:83]
	v_mfma_f32_16x16x32_bf16 v[112:115], v[136:139], v[238:241], v[112:115]
	v_mfma_f32_16x16x32_bf16 v[104:107], v[132:135], v[164:167], v[104:107]
	v_mfma_f32_16x16x32_bf16 v[124:127], v[140:143], v[164:167], v[124:127]
	v_mfma_f32_16x16x32_bf16 v[96:99], v[132:135], v[172:175], v[96:99]
	v_mfma_f32_16x16x32_bf16 v[120:123], v[140:143], v[172:175], v[120:123]
	v_mfma_f32_16x16x32_bf16 v[88:91], v[132:135], v[202:205], v[88:91]
	v_mfma_f32_16x16x32_bf16 v[116:119], v[140:143], v[202:205], v[116:119]
	v_mfma_f32_16x16x32_bf16 v[80:83], v[132:135], v[242:245], v[80:83]
	v_mfma_f32_16x16x32_bf16 v[112:115], v[140:143], v[242:245], v[112:115]
	v_mfma_f32_16x16x32_bf16 v[72:75], v[144:147], v[160:163], v[72:75]
	v_mfma_f32_16x16x32_bf16 v[108:111], v[152:155], v[160:163], v[108:111]
	v_mfma_f32_16x16x32_bf16 v[64:67], v[144:147], v[168:171], v[64:67]
	v_mfma_f32_16x16x32_bf16 v[100:103], v[152:155], v[168:171], v[100:103]
	v_mfma_f32_16x16x32_bf16 v[56:59], v[144:147], v[198:201], v[56:59]
	v_mfma_f32_16x16x32_bf16 v[92:95], v[152:155], v[198:201], v[92:95]
	v_mfma_f32_16x16x32_bf16 v[48:51], v[144:147], v[238:241], v[48:51]
	v_mfma_f32_16x16x32_bf16 v[84:87], v[152:155], v[238:241], v[84:87]
	v_mfma_f32_16x16x32_bf16 v[72:75], v[148:151], v[164:167], v[72:75]
	v_mfma_f32_16x16x32_bf16 v[108:111], v[156:159], v[164:167], v[108:111]
	v_mfma_f32_16x16x32_bf16 v[64:67], v[148:151], v[172:175], v[64:67]
	v_mfma_f32_16x16x32_bf16 v[100:103], v[156:159], v[172:175], v[100:103]
	v_mfma_f32_16x16x32_bf16 v[56:59], v[148:151], v[202:205], v[56:59]
	v_mfma_f32_16x16x32_bf16 v[92:95], v[156:159], v[202:205], v[92:95]
	v_mfma_f32_16x16x32_bf16 v[48:51], v[148:151], v[242:245], v[48:51]
	v_mfma_f32_16x16x32_bf16 v[84:87], v[156:159], v[242:245], v[84:87]
	s_barrier
	s_mov_b32 m0, s31
	v_lshl_add_u64 v[214:215], v[246:247], 0, s[0:1]
	ds_read_b128 v[160:163], v219 offset:49152
	ds_read_b128 v[164:167], v219 offset:50176
	ds_read_b128 v[168:171], v219 offset:51200
	ds_read_b128 v[172:175], v219 offset:52224
	ds_read_b128 v[198:201], v219 offset:53248
	ds_read_b128 v[202:205], v219 offset:54272
	ds_read_b128 v[238:241], v219 offset:55296
	ds_read_b128 v[242:245], v219 offset:56320
	global_load_lds_dwordx4 v[214:215], off
	v_lshl_add_u64 v[214:215], v[248:249], 0, s[0:1]
	s_mov_b32 m0, s30
	s_nop 0
	global_load_lds_dwordx4 v[214:215], off
	s_mov_b32 m0, s95
	s_nop 0
	global_load_lds_dwordx4 v190, s[84:85]
	s_mov_b32 m0, s94
	s_nop 0
	global_load_lds_dwordx4 v186, s[84:85]
	v_lshl_add_u64 v[214:215], v[250:251], 0, s[0:1]
	s_mov_b32 m0, s35
	s_nop 0
	global_load_lds_dwordx4 v[214:215], off
	v_lshl_add_u64 v[214:215], v[252:253], 0, s[0:1]
	s_mov_b32 m0, s34
	s_nop 0
	global_load_lds_dwordx4 v[214:215], off
	s_waitcnt vmcnt(8)
	s_waitcnt lgkmcnt(0)
	s_barrier
	s_waitcnt lgkmcnt(0)
	v_mfma_f32_16x16x32_bf16 v[40:43], v[128:131], v[160:163], v[40:43]
	v_mfma_f32_16x16x32_bf16 v[76:79], v[136:139], v[160:163], v[76:79]
	v_mfma_f32_16x16x32_bf16 v[32:35], v[128:131], v[168:171], v[32:35]
	v_mfma_f32_16x16x32_bf16 v[68:71], v[136:139], v[168:171], v[68:71]
	v_mfma_f32_16x16x32_bf16 v[24:27], v[128:131], v[198:201], v[24:27]
	v_mfma_f32_16x16x32_bf16 v[60:63], v[136:139], v[198:201], v[60:63]
	v_mfma_f32_16x16x32_bf16 v[20:23], v[128:131], v[238:241], v[20:23]
	v_mfma_f32_16x16x32_bf16 v[52:55], v[136:139], v[238:241], v[52:55]
	v_mfma_f32_16x16x32_bf16 v[40:43], v[132:135], v[164:167], v[40:43]
	v_mfma_f32_16x16x32_bf16 v[76:79], v[140:143], v[164:167], v[76:79]
	v_mfma_f32_16x16x32_bf16 v[32:35], v[132:135], v[172:175], v[32:35]
	v_mfma_f32_16x16x32_bf16 v[68:71], v[140:143], v[172:175], v[68:71]
	v_mfma_f32_16x16x32_bf16 v[24:27], v[132:135], v[202:205], v[24:27]
	v_mfma_f32_16x16x32_bf16 v[60:63], v[140:143], v[202:205], v[60:63]
	v_mfma_f32_16x16x32_bf16 v[20:23], v[132:135], v[242:245], v[20:23]
	v_mfma_f32_16x16x32_bf16 v[52:55], v[140:143], v[242:245], v[52:55]
	v_mfma_f32_16x16x32_bf16 v[16:19], v[144:147], v[160:163], v[16:19]
	v_mfma_f32_16x16x32_bf16 v[44:47], v[152:155], v[160:163], v[44:47]
	v_mfma_f32_16x16x32_bf16 v[12:15], v[144:147], v[168:171], v[12:15]
	v_mfma_f32_16x16x32_bf16 v[36:39], v[152:155], v[168:171], v[36:39]
	v_mfma_f32_16x16x32_bf16 v[4:7], v[144:147], v[198:201], v[4:7]
	v_mfma_f32_16x16x32_bf16 v[28:31], v[152:155], v[198:201], v[28:31]
	v_mfma_f32_16x16x32_bf16 v[0:3], v[144:147], v[238:241], v[0:3]
	v_mfma_f32_16x16x32_bf16 v[8:11], v[152:155], v[238:241], v[8:11]
	v_mfma_f32_16x16x32_bf16 v[16:19], v[148:151], v[164:167], v[16:19]
	v_mfma_f32_16x16x32_bf16 v[44:47], v[156:159], v[164:167], v[44:47]
	v_mfma_f32_16x16x32_bf16 v[12:15], v[148:151], v[172:175], v[12:15]
	v_mfma_f32_16x16x32_bf16 v[36:39], v[156:159], v[172:175], v[36:39]
	v_mfma_f32_16x16x32_bf16 v[4:7], v[148:151], v[202:205], v[4:7]
	v_mfma_f32_16x16x32_bf16 v[28:31], v[156:159], v[202:205], v[28:31]
	v_mfma_f32_16x16x32_bf16 v[0:3], v[148:151], v[242:245], v[0:3]
	v_mfma_f32_16x16x32_bf16 v[8:11], v[156:159], v[242:245], v[8:11]
	s_barrier
	s_movk_i32 s2, 0x100
	s_andn2_b64 vcc, exec, s[38:39]
	s_mov_b64 s[84:85], -1
	s_mov_b64 s[38:39], 0
	s_cbranch_vccz .LBB0_42
	s_and_b64 vcc, exec, s[40:41]
	s_cbranch_vccz .LBB0_45
	s_barrier

.LBB0_157:
	v_or_b32_e32 v138, 0x10000, v142
	v_add_u32_e32 v139, 0x10400, v142
	ds_read_b128 v[144:147], v138
	ds_read_b128 v[148:151], v139
	v_add_u32_e32 v138, 0x10800, v142
	v_add_u32_e32 v139, 0x10c00, v142
	ds_read_b128 v[152:155], v138
	ds_read_b128 v[156:159], v139
	v_or_b32_e32 v138, 0x14000, v142
	v_add_u32_e32 v139, 0x14400, v142
	ds_read_b128 v[160:163], v138
	ds_read_b128 v[164:167], v139
	v_add_u32_e32 v138, 0x14800, v142
	v_add_u32_e32 v139, 0x14c00, v142
	ds_read_b128 v[168:171], v138
	ds_read_b128 v[172:175], v139
	s_add_u32 s8, vcc_lo, 0xfffc0080
	s_addc_u32 s9, vcc_hi, -1
	s_cmp_eq_u32 s90, 12
	s_cselect_b32 s11, s5, s9
	s_cselect_b32 s10, s92, s8
	s_cselect_b32 s9, s85, s89
	s_cselect_b32 s8, s96, s88
	s_add_i32 m0, s23, 0xc000
	ds_read_b128 v[186:189], v141
	ds_read_b128 v[190:193], v141 offset:1024
	ds_read_b128 v[194:197], v141 offset:2048
	ds_read_b128 v[198:201], v141 offset:3072
	ds_read_b128 v[202:205], v141 offset:4096
	ds_read_b128 v[220:223], v141 offset:5120
	ds_read_b128 v[224:227], v141 offset:6144
	ds_read_b128 v[228:231], v141 offset:7168
	global_load_lds_dwordx4 v134, vcc
	s_add_i32 m0, s23, 0xe000
	s_nop 0
	global_load_lds_dwordx4 v136, vcc
	s_waitcnt vmcnt(8)
	s_waitcnt lgkmcnt(0)
	s_barrier
	s_waitcnt lgkmcnt(0)
	v_mfma_f32_16x16x32_bf16 v[124:127], v[144:147], v[186:189], v[124:127]
	v_mfma_f32_16x16x32_bf16 v[120:123], v[152:155], v[186:189], v[120:123]
	v_mfma_f32_16x16x32_bf16 v[108:111], v[144:147], v[194:197], v[108:111]
	v_mfma_f32_16x16x32_bf16 v[104:107], v[152:155], v[194:197], v[104:107]
	v_mfma_f32_16x16x32_bf16 v[92:95], v[144:147], v[202:205], v[92:95]
	v_mfma_f32_16x16x32_bf16 v[88:91], v[152:155], v[202:205], v[88:91]
	v_mfma_f32_16x16x32_bf16 v[76:79], v[144:147], v[224:227], v[76:79]
	v_mfma_f32_16x16x32_bf16 v[72:75], v[152:155], v[224:227], v[72:75]
	v_mfma_f32_16x16x32_bf16 v[124:127], v[148:151], v[190:193], v[124:127]
	v_mfma_f32_16x16x32_bf16 v[120:123], v[156:159], v[190:193], v[120:123]
	v_mfma_f32_16x16x32_bf16 v[108:111], v[148:151], v[198:201], v[108:111]
	v_mfma_f32_16x16x32_bf16 v[104:107], v[156:159], v[198:201], v[104:107]
	v_mfma_f32_16x16x32_bf16 v[92:95], v[148:151], v[220:223], v[92:95]
	v_mfma_f32_16x16x32_bf16 v[88:91], v[156:159], v[220:223], v[88:91]
	v_mfma_f32_16x16x32_bf16 v[76:79], v[148:151], v[228:231], v[76:79]
	v_mfma_f32_16x16x32_bf16 v[72:75], v[156:159], v[228:231], v[72:75]
	v_mfma_f32_16x16x32_bf16 v[116:119], v[160:163], v[186:189], v[116:119]
	v_mfma_f32_16x16x32_bf16 v[112:115], v[168:171], v[186:189], v[112:115]
	v_mfma_f32_16x16x32_bf16 v[100:103], v[160:163], v[194:197], v[100:103]
	v_mfma_f32_16x16x32_bf16 v[96:99], v[168:171], v[194:197], v[96:99]
	v_mfma_f32_16x16x32_bf16 v[84:87], v[160:163], v[202:205], v[84:87]
	v_mfma_f32_16x16x32_bf16 v[80:83], v[168:171], v[202:205], v[80:83]
	v_mfma_f32_16x16x32_bf16 v[68:71], v[160:163], v[224:227], v[68:71]
	v_mfma_f32_16x16x32_bf16 v[64:67], v[168:171], v[224:227], v[64:67]
	v_mfma_f32_16x16x32_bf16 v[116:119], v[164:167], v[190:193], v[116:119]
	v_mfma_f32_16x16x32_bf16 v[112:115], v[172:175], v[190:193], v[112:115]
	v_mfma_f32_16x16x32_bf16 v[100:103], v[164:167], v[198:201], v[100:103]
	v_mfma_f32_16x16x32_bf16 v[96:99], v[172:175], v[198:201], v[96:99]
	v_mfma_f32_16x16x32_bf16 v[84:87], v[164:167], v[220:223], v[84:87]
	v_mfma_f32_16x16x32_bf16 v[80:83], v[172:175], v[220:223], v[80:83]
	v_mfma_f32_16x16x32_bf16 v[68:71], v[164:167], v[228:231], v[68:71]
	v_mfma_f32_16x16x32_bf16 v[64:67], v[172:175], v[228:231], v[64:67]
	s_barrier
	s_mov_b32 m0, s25
	v_lshl_add_u64 v[138:139], s[8:9], 0, v[176:177]
	s_add_u32 s60, s8, 0x40000
	ds_read_b128 v[186:189], v141 offset:16384
	ds_read_b128 v[190:193], v141 offset:17408
	ds_read_b128 v[194:197], v141 offset:18432
	ds_read_b128 v[198:201], v141 offset:19456
	ds_read_b128 v[202:205], v141 offset:20480
	ds_read_b128 v[220:223], v141 offset:21504
	ds_read_b128 v[224:227], v141 offset:22528
	ds_read_b128 v[228:231], v141 offset:23552
	global_load_lds_dwordx4 v[138:139], off
	v_lshl_add_u64 v[232:233], s[8:9], 0, v[128:129]
	s_mov_b32 m0, s26
	s_addc_u32 s61, s9, 0
	global_load_lds_dwordx4 v[232:233], off
	s_mov_b32 m0, s27
	v_lshl_add_u64 v[236:237], s[10:11], 0, v[130:131]
	global_load_lds_dwordx4 v176, s[60:61]
	s_mov_b32 m0, s28
	s_nop 0
	global_load_lds_dwordx4 v128, s[60:61]
	v_lshl_add_u64 v[234:235], s[10:11], 0, v[132:133]
	s_mov_b32 m0, s23
	s_nop 0
	global_load_lds_dwordx4 v[234:235], off
	s_mov_b32 m0, s29
	s_nop 0
	global_load_lds_dwordx4 v[236:237], off
	s_waitcnt vmcnt(8)
	s_waitcnt lgkmcnt(0)
	s_barrier
	s_waitcnt lgkmcnt(0)
	v_mfma_f32_16x16x32_bf16 v[60:63], v[144:147], v[186:189], v[60:63]
	v_mfma_f32_16x16x32_bf16 v[56:59], v[152:155], v[186:189], v[56:59]
	v_mfma_f32_16x16x32_bf16 v[44:47], v[144:147], v[194:197], v[44:47]
	v_mfma_f32_16x16x32_bf16 v[40:43], v[152:155], v[194:197], v[40:43]
	v_mfma_f32_16x16x32_bf16 v[28:31], v[144:147], v[202:205], v[28:31]
	v_mfma_f32_16x16x32_bf16 v[24:27], v[152:155], v[202:205], v[24:27]
	v_mfma_f32_16x16x32_bf16 v[12:15], v[144:147], v[224:227], v[12:15]
	v_mfma_f32_16x16x32_bf16 v[8:11], v[152:155], v[224:227], v[8:11]
	v_mfma_f32_16x16x32_bf16 v[60:63], v[148:151], v[190:193], v[60:63]
	v_mfma_f32_16x16x32_bf16 v[56:59], v[156:159], v[190:193], v[56:59]
	v_mfma_f32_16x16x32_bf16 v[44:47], v[148:151], v[198:201], v[44:47]
	v_mfma_f32_16x16x32_bf16 v[40:43], v[156:159], v[198:201], v[40:43]
	v_mfma_f32_16x16x32_bf16 v[28:31], v[148:151], v[220:223], v[28:31]
	v_mfma_f32_16x16x32_bf16 v[24:27], v[156:159], v[220:223], v[24:27]
	v_mfma_f32_16x16x32_bf16 v[12:15], v[148:151], v[228:231], v[12:15]
	v_mfma_f32_16x16x32_bf16 v[8:11], v[156:159], v[228:231], v[8:11]
	v_mfma_f32_16x16x32_bf16 v[52:55], v[160:163], v[186:189], v[52:55]
	v_mfma_f32_16x16x32_bf16 v[48:51], v[168:171], v[186:189], v[48:51]
	v_mfma_f32_16x16x32_bf16 v[36:39], v[160:163], v[194:197], v[36:39]
	v_mfma_f32_16x16x32_bf16 v[32:35], v[168:171], v[194:197], v[32:35]
	v_mfma_f32_16x16x32_bf16 v[20:23], v[160:163], v[202:205], v[20:23]
	v_mfma_f32_16x16x32_bf16 v[16:19], v[168:171], v[202:205], v[16:19]
	v_mfma_f32_16x16x32_bf16 v[4:7], v[160:163], v[224:227], v[4:7]
	v_mfma_f32_16x16x32_bf16 v[0:3], v[168:171], v[224:227], v[0:3]
	v_mfma_f32_16x16x32_bf16 v[52:55], v[164:167], v[190:193], v[52:55]
	v_mfma_f32_16x16x32_bf16 v[48:51], v[172:175], v[190:193], v[48:51]
	v_mfma_f32_16x16x32_bf16 v[36:39], v[164:167], v[198:201], v[36:39]
	v_mfma_f32_16x16x32_bf16 v[32:35], v[172:175], v[198:201], v[32:35]
	v_mfma_f32_16x16x32_bf16 v[20:23], v[164:167], v[220:223], v[20:23]
	v_mfma_f32_16x16x32_bf16 v[16:19], v[172:175], v[220:223], v[16:19]
	v_mfma_f32_16x16x32_bf16 v[4:7], v[164:167], v[228:231], v[4:7]
	v_mfma_f32_16x16x32_bf16 v[0:3], v[172:175], v[228:231], v[0:3]
	s_barrier
	v_or_b32_e32 v144, 0x18000, v142
	v_add_u32_e32 v148, 0x18400, v142
	v_add_u32_e32 v152, 0x18800, v142
	v_add_u32_e32 v156, 0x18c00, v142
	v_or_b32_e32 v160, 0x1c000, v142
	v_add_u32_e32 v164, 0x1c400, v142
	v_add_u32_e32 v168, 0x1c800, v142
	v_add_u32_e32 v172, 0x1cc00, v142
	ds_read_b128 v[144:147], v144
	ds_read_b128 v[148:151], v148
	ds_read_b128 v[152:155], v152
	ds_read_b128 v[156:159], v156
	ds_read_b128 v[160:163], v160
	ds_read_b128 v[164:167], v164
	ds_read_b128 v[168:171], v168
	ds_read_b128 v[172:175], v172
	s_add_u32 s10, s10, 0x40000
	s_addc_u32 s11, s11, 0
	s_mov_b32 m0, s30
	ds_read_b128 v[186:189], v141 offset:32768
	ds_read_b128 v[190:193], v141 offset:33792
	ds_read_b128 v[194:197], v141 offset:34816
	ds_read_b128 v[198:201], v141 offset:35840
	ds_read_b128 v[202:205], v141 offset:36864
	ds_read_b128 v[220:223], v141 offset:37888
	ds_read_b128 v[224:227], v141 offset:38912
	ds_read_b128 v[228:231], v141 offset:39936
	global_load_lds_dwordx4 v132, s[10:11]
	v_lshl_add_u64 v[238:239], s[10:11], 0, v[130:131]
	s_mov_b32 m0, s31
	s_nop 0
	global_load_lds_dwordx4 v[238:239], off
	s_waitcnt vmcnt(8)
	s_waitcnt lgkmcnt(0)
	s_barrier
	s_waitcnt lgkmcnt(0)
	v_mfma_f32_16x16x32_bf16 v[124:127], v[144:147], v[186:189], v[124:127]
	v_mfma_f32_16x16x32_bf16 v[120:123], v[152:155], v[186:189], v[120:123]
	v_mfma_f32_16x16x32_bf16 v[108:111], v[144:147], v[194:197], v[108:111]
	v_mfma_f32_16x16x32_bf16 v[104:107], v[152:155], v[194:197], v[104:107]
	v_mfma_f32_16x16x32_bf16 v[92:95], v[144:147], v[202:205], v[92:95]
	v_mfma_f32_16x16x32_bf16 v[88:91], v[152:155], v[202:205], v[88:91]
	v_mfma_f32_16x16x32_bf16 v[76:79], v[144:147], v[224:227], v[76:79]
	v_mfma_f32_16x16x32_bf16 v[72:75], v[152:155], v[224:227], v[72:75]
	v_mfma_f32_16x16x32_bf16 v[124:127], v[148:151], v[190:193], v[124:127]
	v_mfma_f32_16x16x32_bf16 v[120:123], v[156:159], v[190:193], v[120:123]
	v_mfma_f32_16x16x32_bf16 v[108:111], v[148:151], v[198:201], v[108:111]
	v_mfma_f32_16x16x32_bf16 v[104:107], v[156:159], v[198:201], v[104:107]
	v_mfma_f32_16x16x32_bf16 v[92:95], v[148:151], v[220:223], v[92:95]
	v_mfma_f32_16x16x32_bf16 v[88:91], v[156:159], v[220:223], v[88:91]
	v_mfma_f32_16x16x32_bf16 v[76:79], v[148:151], v[228:231], v[76:79]
	v_mfma_f32_16x16x32_bf16 v[72:75], v[156:159], v[228:231], v[72:75]
	v_mfma_f32_16x16x32_bf16 v[116:119], v[160:163], v[186:189], v[116:119]
	v_mfma_f32_16x16x32_bf16 v[112:115], v[168:171], v[186:189], v[112:115]
	v_mfma_f32_16x16x32_bf16 v[100:103], v[160:163], v[194:197], v[100:103]
	v_mfma_f32_16x16x32_bf16 v[96:99], v[168:171], v[194:197], v[96:99]
	v_mfma_f32_16x16x32_bf16 v[84:87], v[160:163], v[202:205], v[84:87]
	v_mfma_f32_16x16x32_bf16 v[80:83], v[168:171], v[202:205], v[80:83]
	v_mfma_f32_16x16x32_bf16 v[68:71], v[160:163], v[224:227], v[68:71]
	v_mfma_f32_16x16x32_bf16 v[64:67], v[168:171], v[224:227], v[64:67]
	v_mfma_f32_16x16x32_bf16 v[116:119], v[164:167], v[190:193], v[116:119]
	v_mfma_f32_16x16x32_bf16 v[112:115], v[172:175], v[190:193], v[112:115]
	v_mfma_f32_16x16x32_bf16 v[100:103], v[164:167], v[198:201], v[100:103]
	v_mfma_f32_16x16x32_bf16 v[96:99], v[172:175], v[198:201], v[96:99]
	v_mfma_f32_16x16x32_bf16 v[84:87], v[164:167], v[220:223], v[84:87]
	v_mfma_f32_16x16x32_bf16 v[80:83], v[172:175], v[220:223], v[80:83]
	v_mfma_f32_16x16x32_bf16 v[68:71], v[164:167], v[228:231], v[68:71]
	v_mfma_f32_16x16x32_bf16 v[64:67], v[172:175], v[228:231], v[64:67]
	s_barrier
	s_mov_b32 m0, s34
	v_lshl_add_u64 v[138:139], v[138:139], 0, s[0:1]
	s_add_u32 s8, s8, 0x40080
	ds_read_b128 v[186:189], v141 offset:49152
	ds_read_b128 v[190:193], v141 offset:50176
	ds_read_b128 v[194:197], v141 offset:51200
	ds_read_b128 v[198:201], v141 offset:52224
	ds_read_b128 v[202:205], v141 offset:53248
	ds_read_b128 v[220:223], v141 offset:54272
	ds_read_b128 v[224:227], v141 offset:55296
	ds_read_b128 v[228:231], v141 offset:56320
	global_load_lds_dwordx4 v[138:139], off
	v_lshl_add_u64 v[138:139], v[232:233], 0, s[0:1]
	s_mov_b32 m0, s35
	s_addc_u32 s9, s9, 0
	global_load_lds_dwordx4 v[138:139], off
	s_mov_b32 m0, s74
	s_nop 0
	global_load_lds_dwordx4 v176, s[8:9]
	s_mov_b32 m0, s75
	s_nop 0
	global_load_lds_dwordx4 v128, s[8:9]
	v_lshl_add_u64 v[138:139], v[234:235], 0, s[0:1]
	s_mov_b32 m0, s42
	s_nop 0
	global_load_lds_dwordx4 v[138:139], off
	v_lshl_add_u64 v[138:139], v[236:237], 0, s[0:1]
	s_mov_b32 m0, s43
	s_nop 0
	global_load_lds_dwordx4 v[138:139], off
	s_waitcnt vmcnt(8)
	s_waitcnt lgkmcnt(0)
	s_barrier
	s_waitcnt lgkmcnt(0)
	v_mfma_f32_16x16x32_bf16 v[60:63], v[144:147], v[186:189], v[60:63]
	v_mfma_f32_16x16x32_bf16 v[56:59], v[152:155], v[186:189], v[56:59]
	v_mfma_f32_16x16x32_bf16 v[44:47], v[144:147], v[194:197], v[44:47]
	v_mfma_f32_16x16x32_bf16 v[40:43], v[152:155], v[194:197], v[40:43]
	v_mfma_f32_16x16x32_bf16 v[28:31], v[144:147], v[202:205], v[28:31]
	v_mfma_f32_16x16x32_bf16 v[24:27], v[152:155], v[202:205], v[24:27]
	v_mfma_f32_16x16x32_bf16 v[12:15], v[144:147], v[224:227], v[12:15]
	v_mfma_f32_16x16x32_bf16 v[8:11], v[152:155], v[224:227], v[8:11]
	v_mfma_f32_16x16x32_bf16 v[60:63], v[148:151], v[190:193], v[60:63]
	v_mfma_f32_16x16x32_bf16 v[56:59], v[156:159], v[190:193], v[56:59]
	v_mfma_f32_16x16x32_bf16 v[44:47], v[148:151], v[198:201], v[44:47]
	v_mfma_f32_16x16x32_bf16 v[40:43], v[156:159], v[198:201], v[40:43]
	v_mfma_f32_16x16x32_bf16 v[28:31], v[148:151], v[220:223], v[28:31]
	v_mfma_f32_16x16x32_bf16 v[24:27], v[156:159], v[220:223], v[24:27]
	v_mfma_f32_16x16x32_bf16 v[12:15], v[148:151], v[228:231], v[12:15]
	v_mfma_f32_16x16x32_bf16 v[8:11], v[156:159], v[228:231], v[8:11]
	v_mfma_f32_16x16x32_bf16 v[52:55], v[160:163], v[186:189], v[52:55]
	v_mfma_f32_16x16x32_bf16 v[48:51], v[168:171], v[186:189], v[48:51]
	v_mfma_f32_16x16x32_bf16 v[36:39], v[160:163], v[194:197], v[36:39]
	v_mfma_f32_16x16x32_bf16 v[32:35], v[168:171], v[194:197], v[32:35]
	v_mfma_f32_16x16x32_bf16 v[20:23], v[160:163], v[202:205], v[20:23]
	v_mfma_f32_16x16x32_bf16 v[16:19], v[168:171], v[202:205], v[16:19]
	v_mfma_f32_16x16x32_bf16 v[4:7], v[160:163], v[224:227], v[4:7]
	v_mfma_f32_16x16x32_bf16 v[0:3], v[168:171], v[224:227], v[0:3]
	v_mfma_f32_16x16x32_bf16 v[52:55], v[164:167], v[190:193], v[52:55]
	v_mfma_f32_16x16x32_bf16 v[48:51], v[172:175], v[190:193], v[48:51]
	v_mfma_f32_16x16x32_bf16 v[36:39], v[164:167], v[198:201], v[36:39]
	v_mfma_f32_16x16x32_bf16 v[32:35], v[172:175], v[198:201], v[32:35]
	v_mfma_f32_16x16x32_bf16 v[20:23], v[164:167], v[220:223], v[20:23]
	v_mfma_f32_16x16x32_bf16 v[16:19], v[172:175], v[220:223], v[16:19]
	v_mfma_f32_16x16x32_bf16 v[4:7], v[164:167], v[228:231], v[4:7]
	v_mfma_f32_16x16x32_bf16 v[0:3], v[172:175], v[228:231], v[0:3]
	s_barrier
	s_add_i32 s90, s90, 2
	s_add_u32 vcc_lo, vcc_lo, 0x100
	s_addc_u32 vcc_hi, vcc_hi, 0
	s_add_u32 s88, s88, 0x100
	s_addc_u32 s89, s89, 0
	s_cmp_gt_u32 s90, 13
	s_cbranch_scc0 .LBB0_157
	s_and_b64 vcc, exec, s[40:41]
	s_cbranch_vccz .LBB0_160
	s_barrier

.LBB0_326:
	v_or_b32_e32 v13, 0x10000, v12
	v_add_u32_e32 v18, 0x10400, v12
	ds_read_b128 v[14:17], v13
	ds_read_b128 v[18:21], v18
	v_add_u32_e32 v13, 0x10800, v12
	v_add_u32_e32 v26, 0x10c00, v12
	s_add_u32 s2, s40, s90
	ds_read_b128 v[22:25], v13
	ds_read_b128 v[26:29], v26
	v_or_b32_e32 v13, 0x14000, v12
	s_addc_u32 s3, s41, s91
	v_add_u32_e32 v30, 0x14400, v12
	ds_read_b128 v[160:163], v13
	ds_read_b128 v[164:167], v30
	v_add_u32_e32 v13, 0x14800, v12
	s_add_u32 s2, s2, 0x100
	v_add_u32_e32 v30, 0x14c00, v12
	ds_read_b128 v[168:171], v13
	ds_read_b128 v[172:175], v30
	s_addc_u32 s3, s3, 0
	s_add_u32 s60, s75, s90
	s_addc_u32 s61, s83, s91
	s_cmpk_eq_i32 s90, 0x700
	s_cselect_b32 s7, s85, s3
	s_cselect_b32 s6, s92, s2
	s_cselect_b32 s3, s5, s61
	s_cselect_b32 s2, s94, s60
	v_lshl_add_u64 v[30:31], v[6:7], 0, s[90:91]
	s_add_i32 m0, s22, 0xc000
	ds_read_b128 v[186:189], v11
	ds_read_b128 v[194:197], v11 offset:1024
	ds_read_b128 v[198:201], v11 offset:2048
	ds_read_b128 v[202:205], v11 offset:3072
	ds_read_b128 v[220:223], v11 offset:4096
	ds_read_b128 v[224:227], v11 offset:5120
	ds_read_b128 v[228:231], v11 offset:6144
	ds_read_b128 v[232:235], v11 offset:7168
	global_load_lds_dwordx4 v[30:31], off
	v_lshl_add_u64 v[30:31], v[8:9], 0, s[90:91]
	s_add_i32 m0, s22, 0xe000
	s_nop 0
	global_load_lds_dwordx4 v[30:31], off
	s_waitcnt vmcnt(8)
	s_waitcnt lgkmcnt(0)
	s_barrier
	s_waitcnt lgkmcnt(0)
	v_mfma_f32_16x16x32_bf16 v[156:159], v[14:17], v[186:189], v[156:159]
	v_mfma_f32_16x16x32_bf16 v[152:155], v[22:25], v[186:189], v[152:155]
	v_mfma_f32_16x16x32_bf16 v[140:143], v[14:17], v[198:201], v[140:143]
	v_mfma_f32_16x16x32_bf16 v[136:139], v[22:25], v[198:201], v[136:139]
	v_mfma_f32_16x16x32_bf16 v[124:127], v[14:17], v[220:223], v[124:127]
	v_mfma_f32_16x16x32_bf16 v[120:123], v[22:25], v[220:223], v[120:123]
	v_mfma_f32_16x16x32_bf16 v[108:111], v[14:17], v[228:231], v[108:111]
	v_mfma_f32_16x16x32_bf16 v[104:107], v[22:25], v[228:231], v[104:107]
	v_mfma_f32_16x16x32_bf16 v[156:159], v[18:21], v[194:197], v[156:159]
	v_mfma_f32_16x16x32_bf16 v[152:155], v[26:29], v[194:197], v[152:155]
	v_mfma_f32_16x16x32_bf16 v[140:143], v[18:21], v[202:205], v[140:143]
	v_mfma_f32_16x16x32_bf16 v[136:139], v[26:29], v[202:205], v[136:139]
	v_mfma_f32_16x16x32_bf16 v[124:127], v[18:21], v[224:227], v[124:127]
	v_mfma_f32_16x16x32_bf16 v[120:123], v[26:29], v[224:227], v[120:123]
	v_mfma_f32_16x16x32_bf16 v[108:111], v[18:21], v[232:235], v[108:111]
	v_mfma_f32_16x16x32_bf16 v[104:107], v[26:29], v[232:235], v[104:107]
	v_mfma_f32_16x16x32_bf16 v[148:151], v[160:163], v[186:189], v[148:151]
	v_mfma_f32_16x16x32_bf16 v[144:147], v[168:171], v[186:189], v[144:147]
	v_mfma_f32_16x16x32_bf16 v[132:135], v[160:163], v[198:201], v[132:135]
	v_mfma_f32_16x16x32_bf16 v[128:131], v[168:171], v[198:201], v[128:131]
	v_mfma_f32_16x16x32_bf16 v[116:119], v[160:163], v[220:223], v[116:119]
	v_mfma_f32_16x16x32_bf16 v[112:115], v[168:171], v[220:223], v[112:115]
	v_mfma_f32_16x16x32_bf16 v[100:103], v[160:163], v[228:231], v[100:103]
	v_mfma_f32_16x16x32_bf16 v[96:99], v[168:171], v[228:231], v[96:99]
	v_mfma_f32_16x16x32_bf16 v[148:151], v[164:167], v[194:197], v[148:151]
	v_mfma_f32_16x16x32_bf16 v[144:147], v[172:175], v[194:197], v[144:147]
	v_mfma_f32_16x16x32_bf16 v[132:135], v[164:167], v[202:205], v[132:135]
	v_mfma_f32_16x16x32_bf16 v[128:131], v[172:175], v[202:205], v[128:131]
	v_mfma_f32_16x16x32_bf16 v[116:119], v[164:167], v[224:227], v[116:119]
	v_mfma_f32_16x16x32_bf16 v[112:115], v[172:175], v[224:227], v[112:115]
	v_mfma_f32_16x16x32_bf16 v[100:103], v[164:167], v[232:235], v[100:103]
	v_mfma_f32_16x16x32_bf16 v[96:99], v[172:175], v[232:235], v[96:99]
	s_barrier
	s_mov_b32 m0, s23
	v_lshl_add_u64 v[190:191], s[2:3], 0, v[176:177]
	s_add_u32 s60, s2, 0x40000
	ds_read_b128 v[186:189], v11 offset:16384
	ds_read_b128 v[194:197], v11 offset:17408
	ds_read_b128 v[198:201], v11 offset:18432
	ds_read_b128 v[202:205], v11 offset:19456
	ds_read_b128 v[220:223], v11 offset:20480
	ds_read_b128 v[224:227], v11 offset:21504
	ds_read_b128 v[228:231], v11 offset:22528
	ds_read_b128 v[232:235], v11 offset:23552
	global_load_lds_dwordx4 v[190:191], off
	v_lshl_add_u64 v[214:215], s[2:3], 0, v[0:1]
	s_mov_b32 m0, s24
	s_addc_u32 s61, s3, 0
	global_load_lds_dwordx4 v[214:215], off
	s_mov_b32 m0, s25
	v_lshl_add_u64 v[236:237], s[6:7], 0, v[176:177]
	global_load_lds_dwordx4 v176, s[60:61]
	s_mov_b32 m0, s26
	v_lshl_add_u64 v[238:239], s[6:7], 0, v[0:1]
	global_load_lds_dwordx4 v0, s[60:61]
	s_mov_b32 m0, s22
	s_nop 0
	global_load_lds_dwordx4 v[236:237], off
	s_mov_b32 m0, s27
	s_nop 0
	global_load_lds_dwordx4 v[238:239], off
	s_waitcnt vmcnt(8)
	s_waitcnt lgkmcnt(0)
	s_barrier
	s_waitcnt lgkmcnt(0)
	v_mfma_f32_16x16x32_bf16 v[92:95], v[14:17], v[186:189], v[92:95]
	v_mfma_f32_16x16x32_bf16 v[88:91], v[22:25], v[186:189], v[88:91]
	v_mfma_f32_16x16x32_bf16 v[76:79], v[14:17], v[198:201], v[76:79]
	v_mfma_f32_16x16x32_bf16 v[72:75], v[22:25], v[198:201], v[72:75]
	v_mfma_f32_16x16x32_bf16 v[60:63], v[14:17], v[220:223], v[60:63]
	v_mfma_f32_16x16x32_bf16 v[56:59], v[22:25], v[220:223], v[56:59]
	v_mfma_f32_16x16x32_bf16 v[14:17], v[14:17], v[228:231], v[44:47]
	v_mfma_f32_16x16x32_bf16 v[92:95], v[18:21], v[194:197], v[92:95]
	v_mfma_f32_16x16x32_bf16 v[88:91], v[26:29], v[194:197], v[88:91]
	v_mfma_f32_16x16x32_bf16 v[76:79], v[18:21], v[202:205], v[76:79]
	v_mfma_f32_16x16x32_bf16 v[72:75], v[26:29], v[202:205], v[72:75]
	v_mfma_f32_16x16x32_bf16 v[60:63], v[18:21], v[224:227], v[60:63]
	v_mfma_f32_16x16x32_bf16 v[56:59], v[26:29], v[224:227], v[56:59]
	v_mfma_f32_16x16x32_bf16 v[14:17], v[18:21], v[232:235], v[14:17]
	v_mfma_f32_16x16x32_bf16 v[18:21], v[22:25], v[228:231], v[40:43]
	v_mfma_f32_16x16x32_bf16 v[18:21], v[26:29], v[232:235], v[18:21]
	v_mfma_f32_16x16x32_bf16 v[40:43], v[160:163], v[198:201], v[68:71]
	v_mfma_f32_16x16x32_bf16 v[68:71], v[164:167], v[202:205], v[40:43]
	v_mfma_f32_16x16x32_bf16 v[40:43], v[168:171], v[198:201], v[64:67]
	v_mfma_f32_16x16x32_bf16 v[64:67], v[172:175], v[202:205], v[40:43]
	v_mfma_f32_16x16x32_bf16 v[40:43], v[160:163], v[220:223], v[52:55]
	v_mfma_f32_16x16x32_bf16 v[52:55], v[164:167], v[224:227], v[40:43]
	v_mfma_f32_16x16x32_bf16 v[40:43], v[168:171], v[220:223], v[48:51]
	v_mfma_f32_16x16x32_bf16 v[36:39], v[160:163], v[228:231], v[36:39]
	v_mfma_f32_16x16x32_bf16 v[30:33], v[168:171], v[228:231], v[32:35]
	v_mfma_f32_16x16x32_bf16 v[22:25], v[160:163], v[186:189], v[84:87]
	v_mfma_f32_16x16x32_bf16 v[26:29], v[168:171], v[186:189], v[80:83]
	v_mfma_f32_16x16x32_bf16 v[48:51], v[172:175], v[224:227], v[40:43]
	v_mfma_f32_16x16x32_bf16 v[36:39], v[164:167], v[232:235], v[36:39]
	v_mfma_f32_16x16x32_bf16 v[30:33], v[172:175], v[232:235], v[30:33]
	v_mfma_f32_16x16x32_bf16 v[22:25], v[164:167], v[194:197], v[22:25]
	v_mfma_f32_16x16x32_bf16 v[26:29], v[172:175], v[194:197], v[26:29]
	s_barrier
	v_or_b32_e32 v13, 0x18000, v12
	v_add_u32_e32 v34, 0x18400, v12
	ds_read_b128 v[40:43], v13
	ds_read_b128 v[44:47], v34
	v_add_u32_e32 v13, 0x18800, v12
	v_add_u32_e32 v34, 0x18c00, v12
	ds_read_b128 v[80:83], v13
	ds_read_b128 v[84:87], v34
	v_or_b32_e32 v13, 0x1c000, v12
	v_add_u32_e32 v34, 0x1c400, v12
	ds_read_b128 v[160:163], v13
	ds_read_b128 v[164:167], v34
	v_add_u32_e32 v13, 0x1c800, v12
	v_add_u32_e32 v34, 0x1cc00, v12
	ds_read_b128 v[168:171], v13
	ds_read_b128 v[172:175], v34
	s_add_u32 s6, s6, 0x40000
	s_addc_u32 s7, s7, 0
	s_mov_b32 m0, s28
	ds_read_b128 v[186:189], v11 offset:32768
	ds_read_b128 v[194:197], v11 offset:33792
	ds_read_b128 v[198:201], v11 offset:34816
	ds_read_b128 v[202:205], v11 offset:35840
	ds_read_b128 v[220:223], v11 offset:36864
	ds_read_b128 v[224:227], v11 offset:37888
	ds_read_b128 v[228:231], v11 offset:38912
	ds_read_b128 v[232:235], v11 offset:39936
	global_load_lds_dwordx4 v176, s[6:7]
	s_mov_b32 m0, s29
	s_nop 0
	global_load_lds_dwordx4 v0, s[6:7]
	s_waitcnt vmcnt(8)
	s_waitcnt lgkmcnt(0)
	s_barrier
	s_waitcnt lgkmcnt(0)
	v_mfma_f32_16x16x32_bf16 v[156:159], v[40:43], v[186:189], v[156:159]
	v_mfma_f32_16x16x32_bf16 v[152:155], v[80:83], v[186:189], v[152:155]
	v_mfma_f32_16x16x32_bf16 v[140:143], v[40:43], v[198:201], v[140:143]
	v_mfma_f32_16x16x32_bf16 v[136:139], v[80:83], v[198:201], v[136:139]
	v_mfma_f32_16x16x32_bf16 v[124:127], v[40:43], v[220:223], v[124:127]
	v_mfma_f32_16x16x32_bf16 v[120:123], v[80:83], v[220:223], v[120:123]
	v_mfma_f32_16x16x32_bf16 v[108:111], v[40:43], v[228:231], v[108:111]
	v_mfma_f32_16x16x32_bf16 v[104:107], v[80:83], v[228:231], v[104:107]
	v_mfma_f32_16x16x32_bf16 v[156:159], v[44:47], v[194:197], v[156:159]
	v_mfma_f32_16x16x32_bf16 v[152:155], v[84:87], v[194:197], v[152:155]
	v_mfma_f32_16x16x32_bf16 v[140:143], v[44:47], v[202:205], v[140:143]
	v_mfma_f32_16x16x32_bf16 v[136:139], v[84:87], v[202:205], v[136:139]
	v_mfma_f32_16x16x32_bf16 v[124:127], v[44:47], v[224:227], v[124:127]
	v_mfma_f32_16x16x32_bf16 v[120:123], v[84:87], v[224:227], v[120:123]
	v_mfma_f32_16x16x32_bf16 v[108:111], v[44:47], v[232:235], v[108:111]
	v_mfma_f32_16x16x32_bf16 v[104:107], v[84:87], v[232:235], v[104:107]
	v_mfma_f32_16x16x32_bf16 v[148:151], v[160:163], v[186:189], v[148:151]
	v_mfma_f32_16x16x32_bf16 v[144:147], v[168:171], v[186:189], v[144:147]
	v_mfma_f32_16x16x32_bf16 v[132:135], v[160:163], v[198:201], v[132:135]
	v_mfma_f32_16x16x32_bf16 v[128:131], v[168:171], v[198:201], v[128:131]
	v_mfma_f32_16x16x32_bf16 v[116:119], v[160:163], v[220:223], v[116:119]
	v_mfma_f32_16x16x32_bf16 v[112:115], v[168:171], v[220:223], v[112:115]
	v_mfma_f32_16x16x32_bf16 v[100:103], v[160:163], v[228:231], v[100:103]
	v_mfma_f32_16x16x32_bf16 v[96:99], v[168:171], v[228:231], v[96:99]
	v_mfma_f32_16x16x32_bf16 v[148:151], v[164:167], v[194:197], v[148:151]
	v_mfma_f32_16x16x32_bf16 v[144:147], v[172:175], v[194:197], v[144:147]
	v_mfma_f32_16x16x32_bf16 v[132:135], v[164:167], v[202:205], v[132:135]
	v_mfma_f32_16x16x32_bf16 v[128:131], v[172:175], v[202:205], v[128:131]
	v_mfma_f32_16x16x32_bf16 v[116:119], v[164:167], v[224:227], v[116:119]
	v_mfma_f32_16x16x32_bf16 v[112:115], v[172:175], v[224:227], v[112:115]
	v_mfma_f32_16x16x32_bf16 v[100:103], v[164:167], v[232:235], v[100:103]
	v_mfma_f32_16x16x32_bf16 v[96:99], v[172:175], v[232:235], v[96:99]
	s_barrier
	s_mov_b32 m0, s30
	v_lshl_add_u64 v[34:35], v[190:191], 0, s[0:1]
	s_add_u32 s2, s2, 0x40080
	ds_read_b128 v[186:189], v11 offset:49152
	ds_read_b128 v[194:197], v11 offset:50176
	ds_read_b128 v[198:201], v11 offset:51200
	ds_read_b128 v[202:205], v11 offset:52224
	ds_read_b128 v[220:223], v11 offset:53248
	ds_read_b128 v[224:227], v11 offset:54272
	ds_read_b128 v[228:231], v11 offset:55296
	ds_read_b128 v[232:235], v11 offset:56320
	global_load_lds_dwordx4 v[34:35], off
	v_lshl_add_u64 v[34:35], v[214:215], 0, s[0:1]
	s_mov_b32 m0, s31
	s_addc_u32 s3, s3, 0
	global_load_lds_dwordx4 v[34:35], off
	s_mov_b32 m0, s42
	s_nop 0
	global_load_lds_dwordx4 v176, s[2:3]
	s_mov_b32 m0, s43
	s_nop 0
	global_load_lds_dwordx4 v0, s[2:3]
	v_lshl_add_u64 v[34:35], v[236:237], 0, s[0:1]
	s_mov_b32 m0, s34
	s_nop 0
	global_load_lds_dwordx4 v[34:35], off
	v_lshl_add_u64 v[34:35], v[238:239], 0, s[0:1]
	s_mov_b32 m0, s35
	s_nop 0
	global_load_lds_dwordx4 v[34:35], off
	s_waitcnt vmcnt(8)
	s_waitcnt lgkmcnt(0)
	s_barrier
	s_waitcnt lgkmcnt(0)
	v_mfma_f32_16x16x32_bf16 v[92:95], v[40:43], v[186:189], v[92:95]
	v_mfma_f32_16x16x32_bf16 v[76:79], v[40:43], v[198:201], v[76:79]
	v_mfma_f32_16x16x32_bf16 v[60:63], v[40:43], v[220:223], v[60:63]
	v_mfma_f32_16x16x32_bf16 v[14:17], v[40:43], v[228:231], v[14:17]
	v_mfma_f32_16x16x32_bf16 v[92:95], v[44:47], v[194:197], v[92:95]
	v_mfma_f32_16x16x32_bf16 v[88:91], v[80:83], v[186:189], v[88:91]
	v_mfma_f32_16x16x32_bf16 v[76:79], v[44:47], v[202:205], v[76:79]
	v_mfma_f32_16x16x32_bf16 v[72:75], v[80:83], v[198:201], v[72:75]
	v_mfma_f32_16x16x32_bf16 v[60:63], v[44:47], v[224:227], v[60:63]
	v_mfma_f32_16x16x32_bf16 v[56:59], v[80:83], v[220:223], v[56:59]
	v_mfma_f32_16x16x32_bf16 v[44:47], v[44:47], v[232:235], v[14:17]
	v_mfma_f32_16x16x32_bf16 v[14:17], v[80:83], v[228:231], v[18:21]
	v_mfma_f32_16x16x32_bf16 v[88:91], v[84:87], v[194:197], v[88:91]
	v_mfma_f32_16x16x32_bf16 v[72:75], v[84:87], v[202:205], v[72:75]
	v_mfma_f32_16x16x32_bf16 v[56:59], v[84:87], v[224:227], v[56:59]
	v_mfma_f32_16x16x32_bf16 v[40:43], v[84:87], v[232:235], v[14:17]
	v_mfma_f32_16x16x32_bf16 v[14:17], v[160:163], v[186:189], v[22:25]
	v_mfma_f32_16x16x32_bf16 v[84:87], v[164:167], v[194:197], v[14:17]
	v_mfma_f32_16x16x32_bf16 v[14:17], v[168:171], v[186:189], v[26:29]
	v_mfma_f32_16x16x32_bf16 v[80:83], v[172:175], v[194:197], v[14:17]
	v_mfma_f32_16x16x32_bf16 v[14:17], v[160:163], v[198:201], v[68:71]
	v_mfma_f32_16x16x32_bf16 v[68:71], v[164:167], v[202:205], v[14:17]
	v_mfma_f32_16x16x32_bf16 v[14:17], v[168:171], v[198:201], v[64:67]
	v_mfma_f32_16x16x32_bf16 v[64:67], v[172:175], v[202:205], v[14:17]
	v_mfma_f32_16x16x32_bf16 v[14:17], v[160:163], v[220:223], v[52:55]
	v_mfma_f32_16x16x32_bf16 v[52:55], v[164:167], v[224:227], v[14:17]
	v_mfma_f32_16x16x32_bf16 v[14:17], v[168:171], v[220:223], v[48:51]
	v_mfma_f32_16x16x32_bf16 v[48:51], v[172:175], v[224:227], v[14:17]
	v_mfma_f32_16x16x32_bf16 v[14:17], v[160:163], v[228:231], v[36:39]
	v_mfma_f32_16x16x32_bf16 v[36:39], v[164:167], v[232:235], v[14:17]
	v_mfma_f32_16x16x32_bf16 v[14:17], v[168:171], v[228:231], v[30:33]
	v_mfma_f32_16x16x32_bf16 v[32:35], v[172:175], v[232:235], v[14:17]
	s_barrier
	s_add_i32 s95, s95, 2
	s_add_u32 s90, s90, 0x100
	s_addc_u32 s91, s91, 0
	s_cmp_gt_u32 s95, 13
	s_cbranch_scc0 .LBB0_326
	s_add_u32 s2, s75, 0xffffff00
	s_addc_u32 s3, s83, -1
	s_andn2_b64 vcc, exec, s[38:39]
	s_cbranch_vccnz .LBB0_317
	v_mov_b32_e32 v32, 0
	s_mov_b32 s9, s4
	s_mov_b32 s82, s84
	s_mov_b64 s[40:41], s[88:89]
	s_mov_b32 s72, s74
	v_mov_b32_e32 v33, v32
	v_mov_b32_e32 v34, v32
	v_mov_b32_e32 v35, v32
	v_mov_b32_e32 v36, v32
	v_mov_b32_e32 v37, v32
	v_mov_b32_e32 v38, v32
	v_mov_b32_e32 v39, v32
	v_mov_b32_e32 v48, v32
	v_mov_b32_e32 v49, v32
	v_mov_b32_e32 v50, v32
	v_mov_b32_e32 v51, v32
	v_mov_b32_e32 v52, v32
	v_mov_b32_e32 v53, v32
	v_mov_b32_e32 v54, v32
	v_mov_b32_e32 v55, v32
	v_mov_b32_e32 v64, v32
	v_mov_b32_e32 v65, v32
	v_mov_b32_e32 v66, v32
	v_mov_b32_e32 v67, v32
	v_mov_b32_e32 v68, v32
	v_mov_b32_e32 v69, v32
	v_mov_b32_e32 v70, v32
	v_mov_b32_e32 v71, v32
	v_mov_b32_e32 v80, v32
	v_mov_b32_e32 v81, v32
	v_mov_b32_e32 v82, v32
	v_mov_b32_e32 v83, v32
	v_mov_b32_e32 v84, v32
	v_mov_b32_e32 v85, v32
	v_mov_b32_e32 v86, v32
	v_mov_b32_e32 v87, v32
	v_mov_b32_e32 v40, v32
	v_mov_b32_e32 v41, v32
	v_mov_b32_e32 v42, v32
	v_mov_b32_e32 v43, v32
	v_mov_b32_e32 v44, v32
	v_mov_b32_e32 v45, v32
	v_mov_b32_e32 v46, v32
	v_mov_b32_e32 v47, v32
	v_mov_b32_e32 v56, v32
	v_mov_b32_e32 v57, v32
	v_mov_b32_e32 v58, v32
	v_mov_b32_e32 v59, v32
	v_mov_b32_e32 v60, v32
	v_mov_b32_e32 v61, v32
	v_mov_b32_e32 v62, v32
	v_mov_b32_e32 v63, v32
	v_mov_b32_e32 v72, v32
	v_mov_b32_e32 v73, v32
	v_mov_b32_e32 v74, v32
	v_mov_b32_e32 v75, v32
	v_mov_b32_e32 v76, v32
	v_mov_b32_e32 v77, v32
	v_mov_b32_e32 v78, v32
	v_mov_b32_e32 v79, v32
	v_mov_b32_e32 v88, v32
	v_mov_b32_e32 v89, v32
	v_mov_b32_e32 v90, v32
	v_mov_b32_e32 v91, v32
	v_mov_b32_e32 v92, v32
	v_mov_b32_e32 v93, v32
	v_mov_b32_e32 v94, v32
	v_mov_b32_e32 v95, v32
	v_mov_b32_e32 v96, v32
	v_mov_b32_e32 v97, v32
	v_mov_b32_e32 v98, v32
	v_mov_b32_e32 v99, v32
	v_mov_b32_e32 v100, v32
	v_mov_b32_e32 v101, v32
	v_mov_b32_e32 v102, v32
	v_mov_b32_e32 v103, v32
	v_mov_b32_e32 v112, v32
	v_mov_b32_e32 v113, v32
	v_mov_b32_e32 v114, v32
	v_mov_b32_e32 v115, v32
	v_mov_b32_e32 v116, v32
	v_mov_b32_e32 v117, v32
	v_mov_b32_e32 v118, v32
	v_mov_b32_e32 v119, v32
	v_mov_b32_e32 v128, v32
	v_mov_b32_e32 v129, v32
	v_mov_b32_e32 v130, v32
	v_mov_b32_e32 v131, v32
	v_mov_b32_e32 v132, v32
	v_mov_b32_e32 v133, v32
	v_mov_b32_e32 v134, v32
	v_mov_b32_e32 v135, v32
	v_mov_b32_e32 v144, v32
	v_mov_b32_e32 v145, v32
	v_mov_b32_e32 v146, v32
	v_mov_b32_e32 v147, v32
	v_mov_b32_e32 v148, v32
	v_mov_b32_e32 v149, v32
	v_mov_b32_e32 v150, v32
	v_mov_b32_e32 v151, v32
	v_mov_b32_e32 v104, v32
	v_mov_b32_e32 v105, v32
	v_mov_b32_e32 v106, v32
	v_mov_b32_e32 v107, v32
	v_mov_b32_e32 v108, v32
	v_mov_b32_e32 v109, v32
	v_mov_b32_e32 v110, v32
	v_mov_b32_e32 v111, v32
	v_mov_b32_e32 v120, v32
	v_mov_b32_e32 v121, v32
	v_mov_b32_e32 v122, v32
	v_mov_b32_e32 v123, v32
	v_mov_b32_e32 v124, v32
	v_mov_b32_e32 v125, v32
	v_mov_b32_e32 v126, v32
	v_mov_b32_e32 v127, v32
	v_mov_b32_e32 v136, v32
	v_mov_b32_e32 v137, v32
	v_mov_b32_e32 v138, v32
	v_mov_b32_e32 v139, v32
	v_mov_b32_e32 v140, v32
	v_mov_b32_e32 v141, v32
	v_mov_b32_e32 v142, v32
	v_mov_b32_e32 v143, v32
	v_mov_b32_e32 v152, v32
	v_mov_b32_e32 v153, v32
	v_mov_b32_e32 v154, v32
	v_mov_b32_e32 v155, v32
	v_mov_b32_e32 v156, v32
	v_mov_b32_e32 v157, v32
	v_mov_b32_e32 v158, v32
	v_mov_b32_e32 v159, v32
	s_andn2_b64 vcc, exec, s[36:37]
	s_cbranch_vccnz .LBB0_318

.LBB0_438:
	v_or_b32_e32 v143, 0x10000, v140
	v_add_u32_e32 v148, 0x10400, v140
	ds_read_b128 v[144:147], v143
	ds_read_b128 v[148:151], v148
	v_add_u32_e32 v143, 0x10800, v140
	v_add_u32_e32 v156, 0x10c00, v140
	ds_read_b128 v[152:155], v143
	ds_read_b128 v[156:159], v156
	v_or_b32_e32 v143, 0x14000, v140
	v_add_u32_e32 v164, 0x14400, v140
	ds_read_b128 v[160:163], v143
	ds_read_b128 v[164:167], v164
	v_add_u32_e32 v143, 0x14800, v140
	v_add_u32_e32 v172, 0x14c00, v140
	ds_read_b128 v[168:171], v143
	ds_read_b128 v[172:175], v172
	s_add_u32 s2, s90, 0xfffc0080
	s_addc_u32 s3, s91, -1
	s_cmp_eq_u32 s95, 12
	s_cselect_b32 s7, s8, s3
	s_cselect_b32 s6, s9, s2
	s_cselect_b32 s3, s83, s94
	s_cselect_b32 s2, s85, s92
	s_add_i32 m0, s20, 0xc000
	ds_read_b128 v[186:189], v139
	ds_read_b128 v[190:193], v139 offset:1024
	ds_read_b128 v[194:197], v139 offset:2048
	ds_read_b128 v[198:201], v139 offset:3072
	ds_read_b128 v[202:205], v139 offset:4096
	ds_read_b128 v[220:223], v139 offset:5120
	ds_read_b128 v[224:227], v139 offset:6144
	ds_read_b128 v[228:231], v139 offset:7168
	global_load_lds_dwordx4 v134, s[90:91]
	s_add_i32 m0, s20, 0xe000
	s_nop 0
	global_load_lds_dwordx4 v136, s[90:91]
	s_waitcnt vmcnt(8)
	s_waitcnt lgkmcnt(0)
	s_barrier
	s_waitcnt lgkmcnt(0)
	v_mfma_f32_16x16x32_bf16 v[124:127], v[144:147], v[186:189], v[124:127]
	v_mfma_f32_16x16x32_bf16 v[120:123], v[152:155], v[186:189], v[120:123]
	v_mfma_f32_16x16x32_bf16 v[116:119], v[144:147], v[194:197], v[116:119]
	v_mfma_f32_16x16x32_bf16 v[112:115], v[152:155], v[194:197], v[112:115]
	v_mfma_f32_16x16x32_bf16 v[100:103], v[144:147], v[202:205], v[100:103]
	v_mfma_f32_16x16x32_bf16 v[96:99], v[152:155], v[202:205], v[96:99]
	v_mfma_f32_16x16x32_bf16 v[84:87], v[144:147], v[224:227], v[84:87]
	v_mfma_f32_16x16x32_bf16 v[80:83], v[152:155], v[224:227], v[80:83]
	v_mfma_f32_16x16x32_bf16 v[124:127], v[148:151], v[190:193], v[124:127]
	v_mfma_f32_16x16x32_bf16 v[120:123], v[156:159], v[190:193], v[120:123]
	v_mfma_f32_16x16x32_bf16 v[116:119], v[148:151], v[198:201], v[116:119]
	v_mfma_f32_16x16x32_bf16 v[112:115], v[156:159], v[198:201], v[112:115]
	v_mfma_f32_16x16x32_bf16 v[100:103], v[148:151], v[220:223], v[100:103]
	v_mfma_f32_16x16x32_bf16 v[96:99], v[156:159], v[220:223], v[96:99]
	v_mfma_f32_16x16x32_bf16 v[84:87], v[148:151], v[228:231], v[84:87]
	v_mfma_f32_16x16x32_bf16 v[80:83], v[156:159], v[228:231], v[80:83]
	v_mfma_f32_16x16x32_bf16 v[108:111], v[160:163], v[186:189], v[108:111]
	v_mfma_f32_16x16x32_bf16 v[104:107], v[168:171], v[186:189], v[104:107]
	v_mfma_f32_16x16x32_bf16 v[92:95], v[160:163], v[194:197], v[92:95]
	v_mfma_f32_16x16x32_bf16 v[88:91], v[168:171], v[194:197], v[88:91]
	v_mfma_f32_16x16x32_bf16 v[76:79], v[160:163], v[202:205], v[76:79]
	v_mfma_f32_16x16x32_bf16 v[72:75], v[168:171], v[202:205], v[72:75]
	v_mfma_f32_16x16x32_bf16 v[68:71], v[160:163], v[224:227], v[68:71]
	v_mfma_f32_16x16x32_bf16 v[64:67], v[168:171], v[224:227], v[64:67]
	v_mfma_f32_16x16x32_bf16 v[108:111], v[164:167], v[190:193], v[108:111]
	v_mfma_f32_16x16x32_bf16 v[104:107], v[172:175], v[190:193], v[104:107]
	v_mfma_f32_16x16x32_bf16 v[92:95], v[164:167], v[198:201], v[92:95]
	v_mfma_f32_16x16x32_bf16 v[88:91], v[172:175], v[198:201], v[88:91]
	v_mfma_f32_16x16x32_bf16 v[76:79], v[164:167], v[220:223], v[76:79]
	v_mfma_f32_16x16x32_bf16 v[72:75], v[172:175], v[220:223], v[72:75]
	v_mfma_f32_16x16x32_bf16 v[68:71], v[164:167], v[228:231], v[68:71]
	v_mfma_f32_16x16x32_bf16 v[64:67], v[172:175], v[228:231], v[64:67]
	s_barrier
	s_mov_b32 m0, s5
	v_lshl_add_u64 v[232:233], s[2:3], 0, v[176:177]
	s_add_u32 s96, s2, 0x40000
	ds_read_b128 v[186:189], v139 offset:16384
	ds_read_b128 v[190:193], v139 offset:17408
	ds_read_b128 v[194:197], v139 offset:18432
	ds_read_b128 v[198:201], v139 offset:19456
	ds_read_b128 v[202:205], v139 offset:20480
	ds_read_b128 v[220:223], v139 offset:21504
	ds_read_b128 v[224:227], v139 offset:22528
	ds_read_b128 v[228:231], v139 offset:23552
	global_load_lds_dwordx4 v[232:233], off
	v_lshl_add_u64 v[234:235], s[2:3], 0, v[128:129]
	s_mov_b32 m0, s22
	s_addc_u32 s97, s3, 0
	global_load_lds_dwordx4 v[234:235], off
	s_mov_b32 m0, s23
	v_lshl_add_u64 v[238:239], s[6:7], 0, v[130:131]
	global_load_lds_dwordx4 v176, s[96:97]
	s_mov_b32 m0, s24
	s_nop 0
	global_load_lds_dwordx4 v128, s[96:97]
	v_lshl_add_u64 v[236:237], s[6:7], 0, v[132:133]
	s_mov_b32 m0, s20
	s_nop 0
	global_load_lds_dwordx4 v[236:237], off
	s_mov_b32 m0, s25
	s_nop 0
	global_load_lds_dwordx4 v[238:239], off
	s_waitcnt vmcnt(8)
	s_waitcnt lgkmcnt(0)
	s_barrier
	s_waitcnt lgkmcnt(0)
	v_mfma_f32_16x16x32_bf16 v[60:63], v[144:147], v[186:189], v[60:63]
	v_mfma_f32_16x16x32_bf16 v[56:59], v[152:155], v[186:189], v[56:59]
	v_mfma_f32_16x16x32_bf16 v[52:55], v[144:147], v[194:197], v[52:55]
	v_mfma_f32_16x16x32_bf16 v[48:51], v[152:155], v[194:197], v[48:51]
	v_mfma_f32_16x16x32_bf16 v[36:39], v[144:147], v[202:205], v[36:39]
	v_mfma_f32_16x16x32_bf16 v[32:35], v[152:155], v[202:205], v[32:35]
	v_mfma_f32_16x16x32_bf16 v[20:23], v[144:147], v[224:227], v[20:23]
	v_mfma_f32_16x16x32_bf16 v[16:19], v[152:155], v[224:227], v[16:19]
	v_mfma_f32_16x16x32_bf16 v[60:63], v[148:151], v[190:193], v[60:63]
	v_mfma_f32_16x16x32_bf16 v[56:59], v[156:159], v[190:193], v[56:59]
	v_mfma_f32_16x16x32_bf16 v[52:55], v[148:151], v[198:201], v[52:55]
	v_mfma_f32_16x16x32_bf16 v[48:51], v[156:159], v[198:201], v[48:51]
	v_mfma_f32_16x16x32_bf16 v[36:39], v[148:151], v[220:223], v[36:39]
	v_mfma_f32_16x16x32_bf16 v[32:35], v[156:159], v[220:223], v[32:35]
	v_mfma_f32_16x16x32_bf16 v[20:23], v[148:151], v[228:231], v[20:23]
	v_mfma_f32_16x16x32_bf16 v[16:19], v[156:159], v[228:231], v[16:19]
	v_mfma_f32_16x16x32_bf16 v[44:47], v[160:163], v[186:189], v[44:47]
	v_mfma_f32_16x16x32_bf16 v[40:43], v[168:171], v[186:189], v[40:43]
	v_mfma_f32_16x16x32_bf16 v[28:31], v[160:163], v[194:197], v[28:31]
	v_mfma_f32_16x16x32_bf16 v[24:27], v[168:171], v[194:197], v[24:27]
	v_mfma_f32_16x16x32_bf16 v[12:15], v[160:163], v[202:205], v[12:15]
	v_mfma_f32_16x16x32_bf16 v[8:11], v[168:171], v[202:205], v[8:11]
	v_mfma_f32_16x16x32_bf16 v[4:7], v[160:163], v[224:227], v[4:7]
	v_mfma_f32_16x16x32_bf16 v[0:3], v[168:171], v[224:227], v[0:3]
	v_mfma_f32_16x16x32_bf16 v[44:47], v[164:167], v[190:193], v[44:47]
	v_mfma_f32_16x16x32_bf16 v[40:43], v[172:175], v[190:193], v[40:43]
	v_mfma_f32_16x16x32_bf16 v[28:31], v[164:167], v[198:201], v[28:31]
	v_mfma_f32_16x16x32_bf16 v[24:27], v[172:175], v[198:201], v[24:27]
	v_mfma_f32_16x16x32_bf16 v[12:15], v[164:167], v[220:223], v[12:15]
	v_mfma_f32_16x16x32_bf16 v[8:11], v[172:175], v[220:223], v[8:11]
	v_mfma_f32_16x16x32_bf16 v[4:7], v[164:167], v[228:231], v[4:7]
	v_mfma_f32_16x16x32_bf16 v[0:3], v[172:175], v[228:231], v[0:3]
	s_barrier
	v_or_b32_e32 v143, 0x18000, v140
	v_add_u32_e32 v148, 0x18400, v140
	ds_read_b128 v[144:147], v143
	ds_read_b128 v[148:151], v148
	v_add_u32_e32 v143, 0x18800, v140
	v_add_u32_e32 v156, 0x18c00, v140
	ds_read_b128 v[152:155], v143
	ds_read_b128 v[156:159], v156
	v_or_b32_e32 v143, 0x1c000, v140
	v_add_u32_e32 v164, 0x1c400, v140
	ds_read_b128 v[160:163], v143
	ds_read_b128 v[164:167], v164
	v_add_u32_e32 v143, 0x1c800, v140
	v_add_u32_e32 v172, 0x1cc00, v140
	ds_read_b128 v[168:171], v143
	ds_read_b128 v[172:175], v172
	s_add_u32 s6, s6, 0x40000
	s_addc_u32 s7, s7, 0
	s_mov_b32 m0, s26
	ds_read_b128 v[186:189], v139 offset:32768
	ds_read_b128 v[190:193], v139 offset:33792
	ds_read_b128 v[194:197], v139 offset:34816
	ds_read_b128 v[198:201], v139 offset:35840
	ds_read_b128 v[202:205], v139 offset:36864
	ds_read_b128 v[220:223], v139 offset:37888
	ds_read_b128 v[224:227], v139 offset:38912
	ds_read_b128 v[228:231], v139 offset:39936
	global_load_lds_dwordx4 v132, s[6:7]
	v_lshl_add_u64 v[240:241], s[6:7], 0, v[130:131]
	s_mov_b32 m0, s27
	s_nop 0
	global_load_lds_dwordx4 v[240:241], off
	s_waitcnt vmcnt(8)
	s_waitcnt lgkmcnt(0)
	s_barrier
	s_waitcnt lgkmcnt(0)
	v_mfma_f32_16x16x32_bf16 v[124:127], v[144:147], v[186:189], v[124:127]
	v_mfma_f32_16x16x32_bf16 v[120:123], v[152:155], v[186:189], v[120:123]
	v_mfma_f32_16x16x32_bf16 v[116:119], v[144:147], v[194:197], v[116:119]
	v_mfma_f32_16x16x32_bf16 v[112:115], v[152:155], v[194:197], v[112:115]
	v_mfma_f32_16x16x32_bf16 v[100:103], v[144:147], v[202:205], v[100:103]
	v_mfma_f32_16x16x32_bf16 v[96:99], v[152:155], v[202:205], v[96:99]
	v_mfma_f32_16x16x32_bf16 v[84:87], v[144:147], v[224:227], v[84:87]
	v_mfma_f32_16x16x32_bf16 v[80:83], v[152:155], v[224:227], v[80:83]
	v_mfma_f32_16x16x32_bf16 v[124:127], v[148:151], v[190:193], v[124:127]
	v_mfma_f32_16x16x32_bf16 v[120:123], v[156:159], v[190:193], v[120:123]
	v_mfma_f32_16x16x32_bf16 v[116:119], v[148:151], v[198:201], v[116:119]
	v_mfma_f32_16x16x32_bf16 v[112:115], v[156:159], v[198:201], v[112:115]
	v_mfma_f32_16x16x32_bf16 v[100:103], v[148:151], v[220:223], v[100:103]
	v_mfma_f32_16x16x32_bf16 v[96:99], v[156:159], v[220:223], v[96:99]
	v_mfma_f32_16x16x32_bf16 v[84:87], v[148:151], v[228:231], v[84:87]
	v_mfma_f32_16x16x32_bf16 v[80:83], v[156:159], v[228:231], v[80:83]
	v_mfma_f32_16x16x32_bf16 v[108:111], v[160:163], v[186:189], v[108:111]
	v_mfma_f32_16x16x32_bf16 v[104:107], v[168:171], v[186:189], v[104:107]
	v_mfma_f32_16x16x32_bf16 v[92:95], v[160:163], v[194:197], v[92:95]
	v_mfma_f32_16x16x32_bf16 v[88:91], v[168:171], v[194:197], v[88:91]
	v_mfma_f32_16x16x32_bf16 v[76:79], v[160:163], v[202:205], v[76:79]
	v_mfma_f32_16x16x32_bf16 v[72:75], v[168:171], v[202:205], v[72:75]
	v_mfma_f32_16x16x32_bf16 v[68:71], v[160:163], v[224:227], v[68:71]
	v_mfma_f32_16x16x32_bf16 v[64:67], v[168:171], v[224:227], v[64:67]
	v_mfma_f32_16x16x32_bf16 v[108:111], v[164:167], v[190:193], v[108:111]
	v_mfma_f32_16x16x32_bf16 v[104:107], v[172:175], v[190:193], v[104:107]
	v_mfma_f32_16x16x32_bf16 v[92:95], v[164:167], v[198:201], v[92:95]
	v_mfma_f32_16x16x32_bf16 v[88:91], v[172:175], v[198:201], v[88:91]
	v_mfma_f32_16x16x32_bf16 v[76:79], v[164:167], v[220:223], v[76:79]
	v_mfma_f32_16x16x32_bf16 v[72:75], v[172:175], v[220:223], v[72:75]
	v_mfma_f32_16x16x32_bf16 v[68:71], v[164:167], v[228:231], v[68:71]
	v_mfma_f32_16x16x32_bf16 v[64:67], v[172:175], v[228:231], v[64:67]
	s_barrier
	s_mov_b32 m0, s28
	v_lshl_add_u64 v[232:233], v[232:233], 0, s[0:1]
	s_add_u32 s2, s2, 0x40080
	ds_read_b128 v[186:189], v139 offset:49152
	ds_read_b128 v[190:193], v139 offset:50176
	ds_read_b128 v[194:197], v139 offset:51200
	ds_read_b128 v[198:201], v139 offset:52224
	ds_read_b128 v[202:205], v139 offset:53248
	ds_read_b128 v[220:223], v139 offset:54272
	ds_read_b128 v[224:227], v139 offset:55296
	ds_read_b128 v[228:231], v139 offset:56320
	global_load_lds_dwordx4 v[232:233], off
	v_lshl_add_u64 v[232:233], v[234:235], 0, s[0:1]
	s_mov_b32 m0, s29
	s_addc_u32 s3, s3, 0
	global_load_lds_dwordx4 v[232:233], off
	s_mov_b32 m0, s34
	s_nop 0
	global_load_lds_dwordx4 v176, s[2:3]
	s_mov_b32 m0, s35
	s_nop 0
	global_load_lds_dwordx4 v128, s[2:3]
	v_lshl_add_u64 v[232:233], v[236:237], 0, s[0:1]
	s_mov_b32 m0, s30
	s_nop 0
	global_load_lds_dwordx4 v[232:233], off
	v_lshl_add_u64 v[232:233], v[238:239], 0, s[0:1]
	s_mov_b32 m0, s31
	s_nop 0
	global_load_lds_dwordx4 v[232:233], off
	s_waitcnt vmcnt(8)
	s_waitcnt lgkmcnt(0)
	s_barrier
	s_waitcnt lgkmcnt(0)
	v_mfma_f32_16x16x32_bf16 v[60:63], v[144:147], v[186:189], v[60:63]
	v_mfma_f32_16x16x32_bf16 v[56:59], v[152:155], v[186:189], v[56:59]
	v_mfma_f32_16x16x32_bf16 v[52:55], v[144:147], v[194:197], v[52:55]
	v_mfma_f32_16x16x32_bf16 v[48:51], v[152:155], v[194:197], v[48:51]
	v_mfma_f32_16x16x32_bf16 v[36:39], v[144:147], v[202:205], v[36:39]
	v_mfma_f32_16x16x32_bf16 v[32:35], v[152:155], v[202:205], v[32:35]
	v_mfma_f32_16x16x32_bf16 v[20:23], v[144:147], v[224:227], v[20:23]
	v_mfma_f32_16x16x32_bf16 v[16:19], v[152:155], v[224:227], v[16:19]
	v_mfma_f32_16x16x32_bf16 v[60:63], v[148:151], v[190:193], v[60:63]
	v_mfma_f32_16x16x32_bf16 v[56:59], v[156:159], v[190:193], v[56:59]
	v_mfma_f32_16x16x32_bf16 v[52:55], v[148:151], v[198:201], v[52:55]
	v_mfma_f32_16x16x32_bf16 v[48:51], v[156:159], v[198:201], v[48:51]
	v_mfma_f32_16x16x32_bf16 v[36:39], v[148:151], v[220:223], v[36:39]
	v_mfma_f32_16x16x32_bf16 v[32:35], v[156:159], v[220:223], v[32:35]
	v_mfma_f32_16x16x32_bf16 v[20:23], v[148:151], v[228:231], v[20:23]
	v_mfma_f32_16x16x32_bf16 v[16:19], v[156:159], v[228:231], v[16:19]
	v_mfma_f32_16x16x32_bf16 v[44:47], v[160:163], v[186:189], v[44:47]
	v_mfma_f32_16x16x32_bf16 v[40:43], v[168:171], v[186:189], v[40:43]
	v_mfma_f32_16x16x32_bf16 v[28:31], v[160:163], v[194:197], v[28:31]
	v_mfma_f32_16x16x32_bf16 v[24:27], v[168:171], v[194:197], v[24:27]
	v_mfma_f32_16x16x32_bf16 v[12:15], v[160:163], v[202:205], v[12:15]
	v_mfma_f32_16x16x32_bf16 v[8:11], v[168:171], v[202:205], v[8:11]
	v_mfma_f32_16x16x32_bf16 v[4:7], v[160:163], v[224:227], v[4:7]
	v_mfma_f32_16x16x32_bf16 v[0:3], v[168:171], v[224:227], v[0:3]
	v_mfma_f32_16x16x32_bf16 v[44:47], v[164:167], v[190:193], v[44:47]
	v_mfma_f32_16x16x32_bf16 v[40:43], v[172:175], v[190:193], v[40:43]
	v_mfma_f32_16x16x32_bf16 v[28:31], v[164:167], v[198:201], v[28:31]
	v_mfma_f32_16x16x32_bf16 v[24:27], v[172:175], v[198:201], v[24:27]
	v_mfma_f32_16x16x32_bf16 v[12:15], v[164:167], v[220:223], v[12:15]
	v_mfma_f32_16x16x32_bf16 v[8:11], v[172:175], v[220:223], v[8:11]
	v_mfma_f32_16x16x32_bf16 v[4:7], v[164:167], v[228:231], v[4:7]
	v_mfma_f32_16x16x32_bf16 v[0:3], v[172:175], v[228:231], v[0:3]
	s_barrier
	s_add_i32 s95, s95, 2
	s_add_u32 s90, s90, 0x100
	s_addc_u32 s91, s91, 0
	s_add_u32 s92, s92, 0x100
	s_addc_u32 s94, s94, 0
	s_cmp_gt_u32 s95, 13
	s_cbranch_scc0 .LBB0_438
	s_and_b64 vcc, exec, s[74:75]
	s_cbranch_vccz .LBB0_441
	s_barrier

.LBB0_462:
	v_or_b32_e32 v147, 0x10000, v145
	v_add_u32_e32 v152, 0x10400, v145
	ds_read_b128 v[148:151], v147
	ds_read_b128 v[152:155], v152
	v_add_u32_e32 v147, 0x10800, v145
	v_add_u32_e32 v160, 0x10c00, v145
	ds_read_b128 v[156:159], v147
	ds_read_b128 v[160:163], v160
	v_or_b32_e32 v147, 0x14000, v145
	v_add_u32_e32 v168, 0x14400, v145
	ds_read_b128 v[164:167], v147
	ds_read_b128 v[168:171], v168
	v_add_u32_e32 v147, 0x14800, v145
	v_add_u32_e32 v186, 0x14c00, v145
	ds_read_b128 v[172:175], v147
	ds_read_b128 v[186:189], v186
	s_add_u32 s2, s90, 0xfffc0080
	s_addc_u32 s3, s91, -1
	s_cmp_eq_u32 s95, 12
	s_cselect_b32 s7, s72, s3
	s_cselect_b32 s6, s75, s2
	s_cselect_b32 s3, s5, s94
	s_cselect_b32 s2, s85, s92
	s_add_i32 m0, s19, 0xc000
	ds_read_b128 v[190:193], v144
	ds_read_b128 v[194:197], v144 offset:1024
	ds_read_b128 v[198:201], v144 offset:2048
	ds_read_b128 v[202:205], v144 offset:3072
	ds_read_b128 v[220:223], v144 offset:4096
	ds_read_b128 v[224:227], v144 offset:5120
	ds_read_b128 v[228:231], v144 offset:6144
	ds_read_b128 v[232:235], v144 offset:7168
	global_load_lds_dwordx4 v138, s[90:91]
	s_add_i32 m0, s19, 0xe000
	s_nop 0
	global_load_lds_dwordx4 v140, s[90:91]
	s_waitcnt vmcnt(8)
	s_waitcnt lgkmcnt(0)
	s_barrier
	s_waitcnt lgkmcnt(0)
	v_mfma_f32_16x16x32_bf16 v[124:127], v[148:151], v[190:193], v[124:127]
	v_mfma_f32_16x16x32_bf16 v[120:123], v[156:159], v[190:193], v[120:123]
	v_mfma_f32_16x16x32_bf16 v[116:119], v[148:151], v[198:201], v[116:119]
	v_mfma_f32_16x16x32_bf16 v[112:115], v[156:159], v[198:201], v[112:115]
	v_mfma_f32_16x16x32_bf16 v[100:103], v[148:151], v[220:223], v[100:103]
	v_mfma_f32_16x16x32_bf16 v[96:99], v[156:159], v[220:223], v[96:99]
	v_mfma_f32_16x16x32_bf16 v[84:87], v[148:151], v[228:231], v[84:87]
	v_mfma_f32_16x16x32_bf16 v[80:83], v[156:159], v[228:231], v[80:83]
	v_mfma_f32_16x16x32_bf16 v[124:127], v[152:155], v[194:197], v[124:127]
	v_mfma_f32_16x16x32_bf16 v[120:123], v[160:163], v[194:197], v[120:123]
	v_mfma_f32_16x16x32_bf16 v[116:119], v[152:155], v[202:205], v[116:119]
	v_mfma_f32_16x16x32_bf16 v[112:115], v[160:163], v[202:205], v[112:115]
	v_mfma_f32_16x16x32_bf16 v[100:103], v[152:155], v[224:227], v[100:103]
	v_mfma_f32_16x16x32_bf16 v[96:99], v[160:163], v[224:227], v[96:99]
	v_mfma_f32_16x16x32_bf16 v[84:87], v[152:155], v[232:235], v[84:87]
	v_mfma_f32_16x16x32_bf16 v[80:83], v[160:163], v[232:235], v[80:83]
	v_mfma_f32_16x16x32_bf16 v[108:111], v[164:167], v[190:193], v[108:111]
	v_mfma_f32_16x16x32_bf16 v[104:107], v[172:175], v[190:193], v[104:107]
	v_mfma_f32_16x16x32_bf16 v[92:95], v[164:167], v[198:201], v[92:95]
	v_mfma_f32_16x16x32_bf16 v[88:91], v[172:175], v[198:201], v[88:91]
	v_mfma_f32_16x16x32_bf16 v[76:79], v[164:167], v[220:223], v[76:79]
	v_mfma_f32_16x16x32_bf16 v[72:75], v[172:175], v[220:223], v[72:75]
	v_mfma_f32_16x16x32_bf16 v[68:71], v[164:167], v[228:231], v[68:71]
	v_mfma_f32_16x16x32_bf16 v[64:67], v[172:175], v[228:231], v[64:67]
	v_mfma_f32_16x16x32_bf16 v[108:111], v[168:171], v[194:197], v[108:111]
	v_mfma_f32_16x16x32_bf16 v[104:107], v[186:189], v[194:197], v[104:107]
	v_mfma_f32_16x16x32_bf16 v[92:95], v[168:171], v[202:205], v[92:95]
	v_mfma_f32_16x16x32_bf16 v[88:91], v[186:189], v[202:205], v[88:91]
	v_mfma_f32_16x16x32_bf16 v[76:79], v[168:171], v[224:227], v[76:79]
	v_mfma_f32_16x16x32_bf16 v[72:75], v[186:189], v[224:227], v[72:75]
	v_mfma_f32_16x16x32_bf16 v[68:71], v[168:171], v[232:235], v[68:71]
	v_mfma_f32_16x16x32_bf16 v[64:67], v[186:189], v[232:235], v[64:67]
	s_barrier
	s_mov_b32 m0, s20
	v_lshl_add_u64 v[236:237], s[2:3], 0, v[130:131]
	s_add_u32 s96, s2, 0x40000
	ds_read_b128 v[190:193], v144 offset:16384
	ds_read_b128 v[194:197], v144 offset:17408
	ds_read_b128 v[198:201], v144 offset:18432
	ds_read_b128 v[202:205], v144 offset:19456
	ds_read_b128 v[220:223], v144 offset:20480
	ds_read_b128 v[224:227], v144 offset:21504
	ds_read_b128 v[228:231], v144 offset:22528
	ds_read_b128 v[232:235], v144 offset:23552
	global_load_lds_dwordx4 v[236:237], off
	v_lshl_add_u64 v[238:239], s[2:3], 0, v[134:135]
	s_mov_b32 m0, s21
	s_addc_u32 s97, s3, 0
	global_load_lds_dwordx4 v[238:239], off
	s_mov_b32 m0, s22
	v_lshl_add_u64 v[242:243], s[6:7], 0, v[132:133]
	global_load_lds_dwordx4 v130, s[96:97]
	s_mov_b32 m0, s23
	s_nop 0
	global_load_lds_dwordx4 v134, s[96:97]
	v_lshl_add_u64 v[240:241], s[6:7], 0, v[128:129]
	s_mov_b32 m0, s19
	s_nop 0
	global_load_lds_dwordx4 v[240:241], off
	s_mov_b32 m0, s24
	s_nop 0
	global_load_lds_dwordx4 v[242:243], off
	s_waitcnt vmcnt(8)
	s_waitcnt lgkmcnt(0)
	s_barrier
	s_waitcnt lgkmcnt(0)
	v_mfma_f32_16x16x32_bf16 v[60:63], v[148:151], v[190:193], v[60:63]
	v_mfma_f32_16x16x32_bf16 v[56:59], v[156:159], v[190:193], v[56:59]
	v_mfma_f32_16x16x32_bf16 v[52:55], v[148:151], v[198:201], v[52:55]
	v_mfma_f32_16x16x32_bf16 v[48:51], v[156:159], v[198:201], v[48:51]
	v_mfma_f32_16x16x32_bf16 v[36:39], v[148:151], v[220:223], v[36:39]
	v_mfma_f32_16x16x32_bf16 v[32:35], v[156:159], v[220:223], v[32:35]
	v_mfma_f32_16x16x32_bf16 v[20:23], v[148:151], v[228:231], v[20:23]
	v_mfma_f32_16x16x32_bf16 v[16:19], v[156:159], v[228:231], v[16:19]
	v_mfma_f32_16x16x32_bf16 v[60:63], v[152:155], v[194:197], v[60:63]
	v_mfma_f32_16x16x32_bf16 v[56:59], v[160:163], v[194:197], v[56:59]
	v_mfma_f32_16x16x32_bf16 v[52:55], v[152:155], v[202:205], v[52:55]
	v_mfma_f32_16x16x32_bf16 v[48:51], v[160:163], v[202:205], v[48:51]
	v_mfma_f32_16x16x32_bf16 v[36:39], v[152:155], v[224:227], v[36:39]
	v_mfma_f32_16x16x32_bf16 v[32:35], v[160:163], v[224:227], v[32:35]
	v_mfma_f32_16x16x32_bf16 v[20:23], v[152:155], v[232:235], v[20:23]
	v_mfma_f32_16x16x32_bf16 v[16:19], v[160:163], v[232:235], v[16:19]
	v_mfma_f32_16x16x32_bf16 v[44:47], v[164:167], v[190:193], v[44:47]
	v_mfma_f32_16x16x32_bf16 v[40:43], v[172:175], v[190:193], v[40:43]
	v_mfma_f32_16x16x32_bf16 v[28:31], v[164:167], v[198:201], v[28:31]
	v_mfma_f32_16x16x32_bf16 v[24:27], v[172:175], v[198:201], v[24:27]
	v_mfma_f32_16x16x32_bf16 v[12:15], v[164:167], v[220:223], v[12:15]
	v_mfma_f32_16x16x32_bf16 v[8:11], v[172:175], v[220:223], v[8:11]
	v_mfma_f32_16x16x32_bf16 v[4:7], v[164:167], v[228:231], v[4:7]
	v_mfma_f32_16x16x32_bf16 v[0:3], v[172:175], v[228:231], v[0:3]
	v_mfma_f32_16x16x32_bf16 v[44:47], v[168:171], v[194:197], v[44:47]
	v_mfma_f32_16x16x32_bf16 v[40:43], v[186:189], v[194:197], v[40:43]
	v_mfma_f32_16x16x32_bf16 v[28:31], v[168:171], v[202:205], v[28:31]
	v_mfma_f32_16x16x32_bf16 v[24:27], v[186:189], v[202:205], v[24:27]
	v_mfma_f32_16x16x32_bf16 v[12:15], v[168:171], v[224:227], v[12:15]
	v_mfma_f32_16x16x32_bf16 v[8:11], v[186:189], v[224:227], v[8:11]
	v_mfma_f32_16x16x32_bf16 v[4:7], v[168:171], v[232:235], v[4:7]
	v_mfma_f32_16x16x32_bf16 v[0:3], v[186:189], v[232:235], v[0:3]
	s_barrier
	v_or_b32_e32 v147, 0x18000, v145
	v_add_u32_e32 v152, 0x18400, v145
	ds_read_b128 v[148:151], v147
	ds_read_b128 v[152:155], v152
	v_add_u32_e32 v147, 0x18800, v145
	v_add_u32_e32 v160, 0x18c00, v145
	ds_read_b128 v[156:159], v147
	ds_read_b128 v[160:163], v160
	v_or_b32_e32 v147, 0x1c000, v145
	v_add_u32_e32 v168, 0x1c400, v145
	ds_read_b128 v[164:167], v147
	ds_read_b128 v[168:171], v168
	v_add_u32_e32 v147, 0x1c800, v145
	v_add_u32_e32 v186, 0x1cc00, v145
	ds_read_b128 v[172:175], v147
	ds_read_b128 v[186:189], v186
	s_add_u32 s6, s6, 0x40000
	s_addc_u32 s7, s7, 0
	s_mov_b32 m0, s25
	ds_read_b128 v[190:193], v144 offset:32768
	ds_read_b128 v[194:197], v144 offset:33792
	ds_read_b128 v[198:201], v144 offset:34816
	ds_read_b128 v[202:205], v144 offset:35840
	ds_read_b128 v[220:223], v144 offset:36864
	ds_read_b128 v[224:227], v144 offset:37888
	ds_read_b128 v[228:231], v144 offset:38912
	ds_read_b128 v[232:235], v144 offset:39936
	global_load_lds_dwordx4 v128, s[6:7]
	v_lshl_add_u64 v[244:245], s[6:7], 0, v[132:133]
	s_mov_b32 m0, s26
	s_nop 0
	global_load_lds_dwordx4 v[244:245], off
	s_waitcnt vmcnt(8)
	s_waitcnt lgkmcnt(0)
	s_barrier
	s_waitcnt lgkmcnt(0)
	v_mfma_f32_16x16x32_bf16 v[124:127], v[148:151], v[190:193], v[124:127]
	v_mfma_f32_16x16x32_bf16 v[120:123], v[156:159], v[190:193], v[120:123]
	v_mfma_f32_16x16x32_bf16 v[116:119], v[148:151], v[198:201], v[116:119]
	v_mfma_f32_16x16x32_bf16 v[112:115], v[156:159], v[198:201], v[112:115]
	v_mfma_f32_16x16x32_bf16 v[100:103], v[148:151], v[220:223], v[100:103]
	v_mfma_f32_16x16x32_bf16 v[96:99], v[156:159], v[220:223], v[96:99]
	v_mfma_f32_16x16x32_bf16 v[84:87], v[148:151], v[228:231], v[84:87]
	v_mfma_f32_16x16x32_bf16 v[80:83], v[156:159], v[228:231], v[80:83]
	v_mfma_f32_16x16x32_bf16 v[124:127], v[152:155], v[194:197], v[124:127]
	v_mfma_f32_16x16x32_bf16 v[120:123], v[160:163], v[194:197], v[120:123]
	v_mfma_f32_16x16x32_bf16 v[116:119], v[152:155], v[202:205], v[116:119]
	v_mfma_f32_16x16x32_bf16 v[112:115], v[160:163], v[202:205], v[112:115]
	v_mfma_f32_16x16x32_bf16 v[100:103], v[152:155], v[224:227], v[100:103]
	v_mfma_f32_16x16x32_bf16 v[96:99], v[160:163], v[224:227], v[96:99]
	v_mfma_f32_16x16x32_bf16 v[84:87], v[152:155], v[232:235], v[84:87]
	v_mfma_f32_16x16x32_bf16 v[80:83], v[160:163], v[232:235], v[80:83]
	v_mfma_f32_16x16x32_bf16 v[108:111], v[164:167], v[190:193], v[108:111]
	v_mfma_f32_16x16x32_bf16 v[104:107], v[172:175], v[190:193], v[104:107]
	v_mfma_f32_16x16x32_bf16 v[92:95], v[164:167], v[198:201], v[92:95]
	v_mfma_f32_16x16x32_bf16 v[88:91], v[172:175], v[198:201], v[88:91]
	v_mfma_f32_16x16x32_bf16 v[76:79], v[164:167], v[220:223], v[76:79]
	v_mfma_f32_16x16x32_bf16 v[72:75], v[172:175], v[220:223], v[72:75]
	v_mfma_f32_16x16x32_bf16 v[68:71], v[164:167], v[228:231], v[68:71]
	v_mfma_f32_16x16x32_bf16 v[64:67], v[172:175], v[228:231], v[64:67]
	v_mfma_f32_16x16x32_bf16 v[108:111], v[168:171], v[194:197], v[108:111]
	v_mfma_f32_16x16x32_bf16 v[104:107], v[186:189], v[194:197], v[104:107]
	v_mfma_f32_16x16x32_bf16 v[92:95], v[168:171], v[202:205], v[92:95]
	v_mfma_f32_16x16x32_bf16 v[88:91], v[186:189], v[202:205], v[88:91]
	v_mfma_f32_16x16x32_bf16 v[76:79], v[168:171], v[224:227], v[76:79]
	v_mfma_f32_16x16x32_bf16 v[72:75], v[186:189], v[224:227], v[72:75]
	v_mfma_f32_16x16x32_bf16 v[68:71], v[168:171], v[232:235], v[68:71]
	v_mfma_f32_16x16x32_bf16 v[64:67], v[186:189], v[232:235], v[64:67]
	s_barrier
	s_mov_b32 m0, s27
	v_lshl_add_u64 v[236:237], v[236:237], 0, s[0:1]
	s_add_u32 s2, s2, 0x40080
	ds_read_b128 v[190:193], v144 offset:49152
	ds_read_b128 v[194:197], v144 offset:50176
	ds_read_b128 v[198:201], v144 offset:51200
	ds_read_b128 v[202:205], v144 offset:52224
	ds_read_b128 v[220:223], v144 offset:53248
	ds_read_b128 v[224:227], v144 offset:54272
	ds_read_b128 v[228:231], v144 offset:55296
	ds_read_b128 v[232:235], v144 offset:56320
	global_load_lds_dwordx4 v[236:237], off
	v_lshl_add_u64 v[236:237], v[238:239], 0, s[0:1]
	s_mov_b32 m0, s28
	s_addc_u32 s3, s3, 0
	global_load_lds_dwordx4 v[236:237], off
	s_mov_b32 m0, s31
	s_nop 0
	global_load_lds_dwordx4 v130, s[2:3]
	s_mov_b32 m0, s34
	s_nop 0
	global_load_lds_dwordx4 v134, s[2:3]
	v_lshl_add_u64 v[236:237], v[240:241], 0, s[0:1]
	s_mov_b32 m0, s29
	s_nop 0
	global_load_lds_dwordx4 v[236:237], off
	v_lshl_add_u64 v[236:237], v[242:243], 0, s[0:1]
	s_mov_b32 m0, s30
	s_nop 0
	global_load_lds_dwordx4 v[236:237], off
	s_waitcnt vmcnt(8)
	s_waitcnt lgkmcnt(0)
	s_barrier
	s_waitcnt lgkmcnt(0)
	v_mfma_f32_16x16x32_bf16 v[60:63], v[148:151], v[190:193], v[60:63]
	v_mfma_f32_16x16x32_bf16 v[56:59], v[156:159], v[190:193], v[56:59]
	v_mfma_f32_16x16x32_bf16 v[52:55], v[148:151], v[198:201], v[52:55]
	v_mfma_f32_16x16x32_bf16 v[48:51], v[156:159], v[198:201], v[48:51]
	v_mfma_f32_16x16x32_bf16 v[36:39], v[148:151], v[220:223], v[36:39]
	v_mfma_f32_16x16x32_bf16 v[32:35], v[156:159], v[220:223], v[32:35]
	v_mfma_f32_16x16x32_bf16 v[20:23], v[148:151], v[228:231], v[20:23]
	v_mfma_f32_16x16x32_bf16 v[16:19], v[156:159], v[228:231], v[16:19]
	v_mfma_f32_16x16x32_bf16 v[60:63], v[152:155], v[194:197], v[60:63]
	v_mfma_f32_16x16x32_bf16 v[56:59], v[160:163], v[194:197], v[56:59]
	v_mfma_f32_16x16x32_bf16 v[52:55], v[152:155], v[202:205], v[52:55]
	v_mfma_f32_16x16x32_bf16 v[48:51], v[160:163], v[202:205], v[48:51]
	v_mfma_f32_16x16x32_bf16 v[36:39], v[152:155], v[224:227], v[36:39]
	v_mfma_f32_16x16x32_bf16 v[32:35], v[160:163], v[224:227], v[32:35]
	v_mfma_f32_16x16x32_bf16 v[20:23], v[152:155], v[232:235], v[20:23]
	v_mfma_f32_16x16x32_bf16 v[16:19], v[160:163], v[232:235], v[16:19]
	v_mfma_f32_16x16x32_bf16 v[44:47], v[164:167], v[190:193], v[44:47]
	v_mfma_f32_16x16x32_bf16 v[40:43], v[172:175], v[190:193], v[40:43]
	v_mfma_f32_16x16x32_bf16 v[28:31], v[164:167], v[198:201], v[28:31]
	v_mfma_f32_16x16x32_bf16 v[24:27], v[172:175], v[198:201], v[24:27]
	v_mfma_f32_16x16x32_bf16 v[12:15], v[164:167], v[220:223], v[12:15]
	v_mfma_f32_16x16x32_bf16 v[8:11], v[172:175], v[220:223], v[8:11]
	v_mfma_f32_16x16x32_bf16 v[4:7], v[164:167], v[228:231], v[4:7]
	v_mfma_f32_16x16x32_bf16 v[0:3], v[172:175], v[228:231], v[0:3]
	v_mfma_f32_16x16x32_bf16 v[44:47], v[168:171], v[194:197], v[44:47]
	v_mfma_f32_16x16x32_bf16 v[40:43], v[186:189], v[194:197], v[40:43]
	v_mfma_f32_16x16x32_bf16 v[28:31], v[168:171], v[202:205], v[28:31]
	v_mfma_f32_16x16x32_bf16 v[24:27], v[186:189], v[202:205], v[24:27]
	v_mfma_f32_16x16x32_bf16 v[12:15], v[168:171], v[224:227], v[12:15]
	v_mfma_f32_16x16x32_bf16 v[8:11], v[186:189], v[224:227], v[8:11]
	v_mfma_f32_16x16x32_bf16 v[4:7], v[168:171], v[232:235], v[4:7]
	v_mfma_f32_16x16x32_bf16 v[0:3], v[186:189], v[232:235], v[0:3]
	s_barrier
	s_add_i32 s95, s95, 2
	s_add_u32 s90, s90, 0x100
	s_addc_u32 s91, s91, 0
	s_add_u32 s92, s92, 0x100
	s_addc_u32 s94, s94, 0
	s_cmp_gt_u32 s95, 13
	s_cbranch_scc0 .LBB0_462
	s_and_b64 vcc, exec, s[40:41]
	s_cbranch_vccz .LBB0_465
	s_barrier
